# gate pass k-loop: 4 MFMAs issued ahead of each of the two per-iteration barriers
# baseline (speedup 1.0000x reference)
; #define LAS __attribute__((address_space(3)))
; DI void gload_lds16(const void* g, LAS char* l) { __builtin_amdgcn_global_load_lds((const unsigned*)g, (LAS unsigned*)l, 16, 0, 0); }
; template <bool WIDE = false>
; DI void gemm_core(f32x4 (&acc)[4][4], const GOp& g, LAS char* lds, const int tidx, const bool have_first, const bool has_next, const GOp& gn, const bool fw16 = false) {
;     ...
;     for (int kt = 0; kt < nk; ++kt) {
;         if (kt == 0 && have_first && fw16) {
;             asm volatile("s_waitcnt vmcnt(8) lgkmcnt(0)" ::: "memory");
;             __builtin_amdgcn_s_barrier();
;             asm volatile("" ::: "memory");
;         } else {
;             asm volatile("s_waitcnt vmcnt(0)" ::: "memory");
;             __syncthreads();
;         }
;         if (kt + 1 < nk) {
;             LAS char* base = lds + ((kt + 1) & 1) * 32768 + w * 1024;
;             const int kn = ((kt + 1 + g.krot) & (nk - 1)) * 64;
;             const bf16_t* Ak = g.A + kn; const bf16_t* Bk = g.Bt + kn;
; #pragma unroll
;             for (int j = 0; j < 4; ++j) { gload_lds16(Ak + oa[j], base + j * 4096); gload_lds16(Bk + ob[j], base + 16384 + j * 4096); }
;         } else if (has_next) gemm_issue(gn, 0, lds, w, lane);
;         LAS char* st = lds + (kt & 1) * 32768;
;         if constexpr (WIDE) {
;         bf16x8 af[2][4], bfr[2][4];
; #pragma unroll
;         for (int ks = 0; ks < 2; ++ks) {
; #pragma unroll
;             for (int i = 0; i < 4; ++i) af[ks][i] = *(LAS bf16x8*)(st + aoff + i * 2048 + (sw ^ (ks * 64)));
; #pragma unroll
;             for (int i = 0; i < 4; ++i) bfr[ks][i] = *(LAS bf16x8*)(st + boff + i * 2048 + (sw ^ (ks * 64)));
;         }
;         __builtin_amdgcn_sched_barrier(0);
;         __builtin_amdgcn_s_setprio(1);
; #pragma unroll
;         for (int ks = 0; ks < 2; ++ks)
; #pragma unroll
;             for (int mi = 0; mi < 4; ++mi)
; #pragma unroll
;                 for (int ni = 0; ni < 4; ++ni) acc[mi][ni] = __builtin_amdgcn_mfma_f32_16x16x32_bf16(bfr[ks][ni], af[ks][mi], acc[mi][ni], 0, 0, 0);
;         __builtin_amdgcn_s_setprio(0);
.Lgp_k0:
	s_setprio 1
	v_mfma_f32_16x16x32_bf16 v[62:65], v[110:113], v[94:97], 0
	v_mfma_f32_16x16x32_bf16 v[58:61], v[114:117], v[94:97], 0
	v_mfma_f32_16x16x32_bf16 v[54:57], v[118:121], v[94:97], 0
	v_mfma_f32_16x16x32_bf16 v[50:53], v[122:125], v[94:97], 0
	s_setprio 0
	s_barrier
	s_setprio 1
	v_mfma_f32_16x16x32_bf16 v[46:49], v[110:113], v[98:101], 0
	ds_read_b128 v[186:189], v226 offset:32768
	ds_read_b128 v[190:193], v226 offset:34816
	v_mfma_f32_16x16x32_bf16 v[42:45], v[114:117], v[98:101], 0
	ds_read_b128 v[194:197], v226 offset:36864
	ds_read_b128 v[198:201], v226 offset:38912
	v_mfma_f32_16x16x32_bf16 v[38:41], v[118:121], v[98:101], 0
	ds_read_b128 v[202:205], v227 offset:49152
	ds_read_b128 v[206:209], v227 offset:51200
	v_mfma_f32_16x16x32_bf16 v[34:37], v[122:125], v[98:101], 0
	ds_read_b128 v[210:213], v227 offset:53248
	ds_read_b128 v[214:217], v227 offset:55296
	v_mfma_f32_16x16x32_bf16 v[30:33], v[110:113], v[102:105], 0
	ds_read_b128 v[218:221], v91 offset:32768
	ds_read_b128 v[222:225], v91 offset:34816
	v_mfma_f32_16x16x32_bf16 v[26:29], v[114:117], v[102:105], 0
	ds_read_b128 v[78:81], v91 offset:36864
	ds_read_b128 v[82:85], v91 offset:38912
	v_mfma_f32_16x16x32_bf16 v[22:25], v[118:121], v[102:105], 0
	ds_read_b128 a[0:3], v92 offset:49152
	ds_read_b128 a[4:7], v92 offset:51200
	v_mfma_f32_16x16x32_bf16 v[18:21], v[122:125], v[102:105], 0
	ds_read_b128 a[8:11], v92 offset:53248
	ds_read_b128 a[12:15], v92 offset:55296
	v_mfma_f32_16x16x32_bf16 v[14:17], v[110:113], v[106:109], 0
	v_mfma_f32_16x16x32_bf16 v[10:13], v[114:117], v[106:109], 0
	v_mfma_f32_16x16x32_bf16 v[6:9], v[118:121], v[106:109], 0
	v_mfma_f32_16x16x32_bf16 v[2:5], v[122:125], v[106:109], 0
	v_mfma_f32_16x16x32_bf16 v[62:65], v[142:145], v[126:129], v[62:65]
	v_mfma_f32_16x16x32_bf16 v[58:61], v[152:155], v[126:129], v[58:61]
	v_mfma_f32_16x16x32_bf16 v[54:57], v[156:159], v[126:129], v[54:57]
	v_mfma_f32_16x16x32_bf16 v[50:53], v[178:181], v[126:129], v[50:53]
	s_setprio 0
	s_waitcnt lgkmcnt(0)
	s_barrier
	s_and_b32 s4, s34, 0x3c0
	s_lshl_b32 s6, s4, 1
	s_add_u32 s4, s39, s6
	s_addc_u32 s5, s45, 0
	s_add_u32 s6, s49, s6
	s_addc_u32 s7, s51, 0
	s_add_i32 s34, s34, 64
	s_setprio 1
	s_add_u32 m0, s100, 0x8000
	v_mfma_f32_16x16x32_bf16 v[46:49], v[142:145], v[130:133], v[46:49]
	global_load_lds_dwordx4 v70, s[4:5]
	s_add_u32 m0, s100, 0xc000
	v_mfma_f32_16x16x32_bf16 v[42:45], v[152:155], v[130:133], v[42:45]
	global_load_lds_dwordx4 v70, s[6:7]
	s_add_u32 m0, s100, 0x9000
	v_mfma_f32_16x16x32_bf16 v[38:41], v[156:159], v[130:133], v[38:41]
	global_load_lds_dwordx4 v72, s[4:5]
	s_add_u32 m0, s100, 0xd000
	v_mfma_f32_16x16x32_bf16 v[34:37], v[178:181], v[130:133], v[34:37]
	global_load_lds_dwordx4 v72, s[6:7]
	s_add_u32 m0, s100, 0xa000
	v_mfma_f32_16x16x32_bf16 v[30:33], v[142:145], v[134:137], v[30:33]
	global_load_lds_dwordx4 v74, s[4:5]
	s_add_u32 m0, s100, 0xe000
	v_mfma_f32_16x16x32_bf16 v[26:29], v[152:155], v[134:137], v[26:29]
	global_load_lds_dwordx4 v74, s[6:7]
	s_add_u32 m0, s100, 0xb000
	v_mfma_f32_16x16x32_bf16 v[22:25], v[156:159], v[134:137], v[22:25]
	global_load_lds_dwordx4 v76, s[4:5]
	s_add_u32 m0, s100, 0xf000
	v_mfma_f32_16x16x32_bf16 v[18:21], v[178:181], v[134:137], v[18:21]
	global_load_lds_dwordx4 v76, s[6:7]
	v_mfma_f32_16x16x32_bf16 v[14:17], v[142:145], v[138:141], v[14:17]
	v_mfma_f32_16x16x32_bf16 v[10:13], v[152:155], v[138:141], v[10:13]
	v_mfma_f32_16x16x32_bf16 v[6:9], v[156:159], v[138:141], v[6:9]
	v_mfma_f32_16x16x32_bf16 v[2:5], v[178:181], v[138:141], v[2:5]
	s_setprio 0
	s_setprio 1
	v_mfma_f32_16x16x32_bf16 v[62:65], v[202:205], v[186:189], v[62:65]
	v_mfma_f32_16x16x32_bf16 v[58:61], v[206:209], v[186:189], v[58:61]
	v_mfma_f32_16x16x32_bf16 v[54:57], v[210:213], v[186:189], v[54:57]
	v_mfma_f32_16x16x32_bf16 v[50:53], v[214:217], v[186:189], v[50:53]
	s_setprio 0
	s_waitcnt vmcnt(8)
	s_barrier
	s_setprio 1
	v_mfma_f32_16x16x32_bf16 v[46:49], v[202:205], v[190:193], v[46:49]
	ds_read_b128 v[94:97], v226 offset:0
	ds_read_b128 v[98:101], v226 offset:2048
	v_mfma_f32_16x16x32_bf16 v[42:45], v[206:209], v[190:193], v[42:45]
	ds_read_b128 v[102:105], v226 offset:4096
	ds_read_b128 v[106:109], v226 offset:6144
	v_mfma_f32_16x16x32_bf16 v[38:41], v[210:213], v[190:193], v[38:41]
	ds_read_b128 v[110:113], v227 offset:16384
	ds_read_b128 v[114:117], v227 offset:18432
	v_mfma_f32_16x16x32_bf16 v[34:37], v[214:217], v[190:193], v[34:37]
	ds_read_b128 v[118:121], v227 offset:20480
	ds_read_b128 v[122:125], v227 offset:22528
	v_mfma_f32_16x16x32_bf16 v[30:33], v[202:205], v[194:197], v[30:33]
	ds_read_b128 v[126:129], v91 offset:0
	ds_read_b128 v[130:133], v91 offset:2048
	v_mfma_f32_16x16x32_bf16 v[26:29], v[206:209], v[194:197], v[26:29]
	ds_read_b128 v[134:137], v91 offset:4096
	ds_read_b128 v[138:141], v91 offset:6144
	v_mfma_f32_16x16x32_bf16 v[22:25], v[210:213], v[194:197], v[22:25]
	ds_read_b128 v[142:145], v92 offset:16384
	ds_read_b128 v[152:155], v92 offset:18432
	v_mfma_f32_16x16x32_bf16 v[18:21], v[214:217], v[194:197], v[18:21]
	ds_read_b128 v[156:159], v92 offset:20480
	ds_read_b128 v[178:181], v92 offset:22528
	v_mfma_f32_16x16x32_bf16 v[14:17], v[202:205], v[198:201], v[14:17]
	v_mfma_f32_16x16x32_bf16 v[10:13], v[206:209], v[198:201], v[10:13]
	v_mfma_f32_16x16x32_bf16 v[6:9], v[210:213], v[198:201], v[6:9]
	v_mfma_f32_16x16x32_bf16 v[2:5], v[214:217], v[198:201], v[2:5]
	v_mfma_f32_16x16x32_bf16 v[62:65], a[0:3], v[218:221], v[62:65]
	v_mfma_f32_16x16x32_bf16 v[58:61], a[4:7], v[218:221], v[58:61]
	v_mfma_f32_16x16x32_bf16 v[54:57], a[8:11], v[218:221], v[54:57]
	v_mfma_f32_16x16x32_bf16 v[50:53], a[12:15], v[218:221], v[50:53]
	s_setprio 0
	s_waitcnt lgkmcnt(0)
	s_barrier
; #define LAS __attribute__((address_space(3)))
; DI void gload_lds16(const void* g, LAS char* l) { __builtin_amdgcn_global_load_lds((const unsigned*)g, (LAS unsigned*)l, 16, 0, 0); }
; template <bool WIDE = false>
; DI void gemm_core(f32x4 (&acc)[4][4], const GOp& g, LAS char* lds, const int tidx, const bool have_first, const bool has_next, const GOp& gn, const bool fw16 = false) {
;     ...
;     for (int kt = 0; kt < nk; ++kt) {
;         if (kt == 0 && have_first && fw16) {
;             asm volatile("s_waitcnt vmcnt(8) lgkmcnt(0)" ::: "memory");
;             __builtin_amdgcn_s_barrier();
;             asm volatile("" ::: "memory");
;         } else {
;             asm volatile("s_waitcnt vmcnt(0)" ::: "memory");
;             __syncthreads();
;         }
;         if (kt + 1 < nk) {
;             LAS char* base = lds + ((kt + 1) & 1) * 32768 + w * 1024;
;             const int kn = ((kt + 1 + g.krot) & (nk - 1)) * 64;
;             const bf16_t* Ak = g.A + kn; const bf16_t* Bk = g.Bt + kn;
; #pragma unroll
;             for (int j = 0; j < 4; ++j) { gload_lds16(Ak + oa[j], base + j * 4096); gload_lds16(Bk + ob[j], base + 16384 + j * 4096); }
;         } else if (has_next) gemm_issue(gn, 0, lds, w, lane);
;         LAS char* st = lds + (kt & 1) * 32768;
;         if constexpr (WIDE) {
;         bf16x8 af[2][4], bfr[2][4];
; #pragma unroll
;         for (int ks = 0; ks < 2; ++ks) {
; #pragma unroll
;             for (int i = 0; i < 4; ++i) af[ks][i] = *(LAS bf16x8*)(st + aoff + i * 2048 + (sw ^ (ks * 64)));
; #pragma unroll
;             for (int i = 0; i < 4; ++i) bfr[ks][i] = *(LAS bf16x8*)(st + boff + i * 2048 + (sw ^ (ks * 64)));
;         }
;         __builtin_amdgcn_sched_barrier(0);
;         __builtin_amdgcn_s_setprio(1);
; #pragma unroll
;         for (int ks = 0; ks < 2; ++ks)
; #pragma unroll
;             for (int mi = 0; mi < 4; ++mi)
; #pragma unroll
;                 for (int ni = 0; ni < 4; ++ni) acc[mi][ni] = __builtin_amdgcn_mfma_f32_16x16x32_bf16(bfr[ks][ni], af[ks][mi], acc[mi][ni], 0, 0, 0);
;         __builtin_amdgcn_s_setprio(0);
	s_and_b32 s4, s34, 0x3c0
	s_lshl_b32 s6, s4, 1
	s_add_u32 s4, s39, s6
	s_addc_u32 s5, s45, 0
	s_add_u32 s6, s49, s6
	s_addc_u32 s7, s51, 0
	s_add_i32 s34, s34, 64
	s_setprio 1
	s_add_u32 m0, s100, 0x0
	v_mfma_f32_16x16x32_bf16 v[46:49], a[0:3], v[222:225], v[46:49]
	global_load_lds_dwordx4 v70, s[4:5]
	s_add_u32 m0, s100, 0x4000
	v_mfma_f32_16x16x32_bf16 v[42:45], a[4:7], v[222:225], v[42:45]
	global_load_lds_dwordx4 v70, s[6:7]
	s_add_u32 m0, s100, 0x1000
	v_mfma_f32_16x16x32_bf16 v[38:41], a[8:11], v[222:225], v[38:41]
	global_load_lds_dwordx4 v72, s[4:5]
	s_add_u32 m0, s100, 0x5000
	v_mfma_f32_16x16x32_bf16 v[34:37], a[12:15], v[222:225], v[34:37]
	global_load_lds_dwordx4 v72, s[6:7]
	s_add_u32 m0, s100, 0x2000
	v_mfma_f32_16x16x32_bf16 v[30:33], a[0:3], v[78:81], v[30:33]
	global_load_lds_dwordx4 v74, s[4:5]
	s_add_u32 m0, s100, 0x6000
	v_mfma_f32_16x16x32_bf16 v[26:29], a[4:7], v[78:81], v[26:29]
	global_load_lds_dwordx4 v74, s[6:7]
	s_add_u32 m0, s100, 0x3000
	v_mfma_f32_16x16x32_bf16 v[22:25], a[8:11], v[78:81], v[22:25]
	global_load_lds_dwordx4 v76, s[4:5]
	s_add_u32 m0, s100, 0x7000
	v_mfma_f32_16x16x32_bf16 v[18:21], a[12:15], v[78:81], v[18:21]
	global_load_lds_dwordx4 v76, s[6:7]
	v_mfma_f32_16x16x32_bf16 v[14:17], a[0:3], v[82:85], v[14:17]
	v_mfma_f32_16x16x32_bf16 v[10:13], a[4:7], v[82:85], v[10:13]
	v_mfma_f32_16x16x32_bf16 v[6:9], a[8:11], v[82:85], v[6:9]
	v_mfma_f32_16x16x32_bf16 v[2:5], a[12:15], v[82:85], v[2:5]
	s_setprio 0
	s_mov_b32 s46, 5
.Lgp_loop:
	s_setprio 1
	v_mfma_f32_16x16x32_bf16 v[62:65], v[110:113], v[94:97], v[62:65]
	v_mfma_f32_16x16x32_bf16 v[58:61], v[114:117], v[94:97], v[58:61]
	v_mfma_f32_16x16x32_bf16 v[54:57], v[118:121], v[94:97], v[54:57]
	v_mfma_f32_16x16x32_bf16 v[50:53], v[122:125], v[94:97], v[50:53]
	s_setprio 0
	s_waitcnt vmcnt(8)
	s_barrier
	s_setprio 1
	v_mfma_f32_16x16x32_bf16 v[46:49], v[110:113], v[98:101], v[46:49]
	ds_read_b128 v[186:189], v226 offset:32768
	ds_read_b128 v[190:193], v226 offset:34816
	v_mfma_f32_16x16x32_bf16 v[42:45], v[114:117], v[98:101], v[42:45]
	ds_read_b128 v[194:197], v226 offset:36864
	ds_read_b128 v[198:201], v226 offset:38912
	v_mfma_f32_16x16x32_bf16 v[38:41], v[118:121], v[98:101], v[38:41]
	ds_read_b128 v[202:205], v227 offset:49152
	ds_read_b128 v[206:209], v227 offset:51200
	v_mfma_f32_16x16x32_bf16 v[34:37], v[122:125], v[98:101], v[34:37]
	ds_read_b128 v[210:213], v227 offset:53248
	ds_read_b128 v[214:217], v227 offset:55296
	v_mfma_f32_16x16x32_bf16 v[30:33], v[110:113], v[102:105], v[30:33]
	ds_read_b128 v[218:221], v91 offset:32768
	ds_read_b128 v[222:225], v91 offset:34816
	v_mfma_f32_16x16x32_bf16 v[26:29], v[114:117], v[102:105], v[26:29]
	ds_read_b128 v[78:81], v91 offset:36864
	ds_read_b128 v[82:85], v91 offset:38912
	v_mfma_f32_16x16x32_bf16 v[22:25], v[118:121], v[102:105], v[22:25]
	ds_read_b128 a[0:3], v92 offset:49152
	ds_read_b128 a[4:7], v92 offset:51200
	v_mfma_f32_16x16x32_bf16 v[18:21], v[122:125], v[102:105], v[18:21]
	ds_read_b128 a[8:11], v92 offset:53248
	ds_read_b128 a[12:15], v92 offset:55296
	v_mfma_f32_16x16x32_bf16 v[14:17], v[110:113], v[106:109], v[14:17]
	v_mfma_f32_16x16x32_bf16 v[10:13], v[114:117], v[106:109], v[10:13]
	v_mfma_f32_16x16x32_bf16 v[6:9], v[118:121], v[106:109], v[6:9]
	v_mfma_f32_16x16x32_bf16 v[2:5], v[122:125], v[106:109], v[2:5]
	v_mfma_f32_16x16x32_bf16 v[62:65], v[142:145], v[126:129], v[62:65]
	v_mfma_f32_16x16x32_bf16 v[58:61], v[152:155], v[126:129], v[58:61]
	v_mfma_f32_16x16x32_bf16 v[54:57], v[156:159], v[126:129], v[54:57]
	v_mfma_f32_16x16x32_bf16 v[50:53], v[178:181], v[126:129], v[50:53]
	s_setprio 0
	s_waitcnt lgkmcnt(0)
	s_barrier
	s_and_b32 s4, s34, 0x3c0
	s_lshl_b32 s6, s4, 1
	s_add_u32 s4, s39, s6
	s_addc_u32 s5, s45, 0
	s_add_u32 s6, s49, s6
	s_addc_u32 s7, s51, 0
	s_add_i32 s34, s34, 64
	s_setprio 1
	s_add_u32 m0, s100, 0x8000
	v_mfma_f32_16x16x32_bf16 v[46:49], v[142:145], v[130:133], v[46:49]
	global_load_lds_dwordx4 v70, s[4:5]
	s_add_u32 m0, s100, 0xc000
	v_mfma_f32_16x16x32_bf16 v[42:45], v[152:155], v[130:133], v[42:45]
	global_load_lds_dwordx4 v70, s[6:7]
	s_add_u32 m0, s100, 0x9000
	v_mfma_f32_16x16x32_bf16 v[38:41], v[156:159], v[130:133], v[38:41]
	global_load_lds_dwordx4 v72, s[4:5]
	s_add_u32 m0, s100, 0xd000
	v_mfma_f32_16x16x32_bf16 v[34:37], v[178:181], v[130:133], v[34:37]
	global_load_lds_dwordx4 v72, s[6:7]
	s_add_u32 m0, s100, 0xa000
	v_mfma_f32_16x16x32_bf16 v[30:33], v[142:145], v[134:137], v[30:33]
	global_load_lds_dwordx4 v74, s[4:5]
	s_add_u32 m0, s100, 0xe000
	v_mfma_f32_16x16x32_bf16 v[26:29], v[152:155], v[134:137], v[26:29]
	global_load_lds_dwordx4 v74, s[6:7]
	s_add_u32 m0, s100, 0xb000
	v_mfma_f32_16x16x32_bf16 v[22:25], v[156:159], v[134:137], v[22:25]
	global_load_lds_dwordx4 v76, s[4:5]
	s_add_u32 m0, s100, 0xf000
	v_mfma_f32_16x16x32_bf16 v[18:21], v[178:181], v[134:137], v[18:21]
	global_load_lds_dwordx4 v76, s[6:7]
	v_mfma_f32_16x16x32_bf16 v[14:17], v[142:145], v[138:141], v[14:17]
	v_mfma_f32_16x16x32_bf16 v[10:13], v[152:155], v[138:141], v[10:13]
	v_mfma_f32_16x16x32_bf16 v[6:9], v[156:159], v[138:141], v[6:9]
	v_mfma_f32_16x16x32_bf16 v[2:5], v[178:181], v[138:141], v[2:5]
	s_setprio 0
	s_setprio 1
	v_mfma_f32_16x16x32_bf16 v[62:65], v[202:205], v[186:189], v[62:65]
	v_mfma_f32_16x16x32_bf16 v[58:61], v[206:209], v[186:189], v[58:61]
	v_mfma_f32_16x16x32_bf16 v[54:57], v[210:213], v[186:189], v[54:57]
	v_mfma_f32_16x16x32_bf16 v[50:53], v[214:217], v[186:189], v[50:53]
	s_setprio 0
	s_waitcnt vmcnt(8)
	s_barrier
; #define LAS __attribute__((address_space(3)))
; DI void gload_lds16(const void* g, LAS char* l) { __builtin_amdgcn_global_load_lds((const unsigned*)g, (LAS unsigned*)l, 16, 0, 0); }
; template <bool WIDE = false>
; DI void gemm_core(f32x4 (&acc)[4][4], const GOp& g, LAS char* lds, const int tidx, const bool have_first, const bool has_next, const GOp& gn, const bool fw16 = false) {
;     ...
;     for (int kt = 0; kt < nk; ++kt) {
;         if (kt == 0 && have_first && fw16) {
;             asm volatile("s_waitcnt vmcnt(8) lgkmcnt(0)" ::: "memory");
;             __builtin_amdgcn_s_barrier();
;             asm volatile("" ::: "memory");
;         } else {
;             asm volatile("s_waitcnt vmcnt(0)" ::: "memory");
;             __syncthreads();
;         }
;         if (kt + 1 < nk) {
;             LAS char* base = lds + ((kt + 1) & 1) * 32768 + w * 1024;
;             const int kn = ((kt + 1 + g.krot) & (nk - 1)) * 64;
;             const bf16_t* Ak = g.A + kn; const bf16_t* Bk = g.Bt + kn;
; #pragma unroll
;             for (int j = 0; j < 4; ++j) { gload_lds16(Ak + oa[j], base + j * 4096); gload_lds16(Bk + ob[j], base + 16384 + j * 4096); }
;         } else if (has_next) gemm_issue(gn, 0, lds, w, lane);
;         LAS char* st = lds + (kt & 1) * 32768;
;         if constexpr (WIDE) {
;         bf16x8 af[2][4], bfr[2][4];
; #pragma unroll
;         for (int ks = 0; ks < 2; ++ks) {
; #pragma unroll
;             for (int i = 0; i < 4; ++i) af[ks][i] = *(LAS bf16x8*)(st + aoff + i * 2048 + (sw ^ (ks * 64)));
; #pragma unroll
;             for (int i = 0; i < 4; ++i) bfr[ks][i] = *(LAS bf16x8*)(st + boff + i * 2048 + (sw ^ (ks * 64)));
;         }
;         __builtin_amdgcn_sched_barrier(0);
;         __builtin_amdgcn_s_setprio(1);
; #pragma unroll
;         for (int ks = 0; ks < 2; ++ks)
; #pragma unroll
;             for (int mi = 0; mi < 4; ++mi)
; #pragma unroll
;                 for (int ni = 0; ni < 4; ++ni) acc[mi][ni] = __builtin_amdgcn_mfma_f32_16x16x32_bf16(bfr[ks][ni], af[ks][mi], acc[mi][ni], 0, 0, 0);
;         __builtin_amdgcn_s_setprio(0);
	s_setprio 1
	v_mfma_f32_16x16x32_bf16 v[46:49], v[202:205], v[190:193], v[46:49]
	ds_read_b128 v[94:97], v226 offset:0
	ds_read_b128 v[98:101], v226 offset:2048
	v_mfma_f32_16x16x32_bf16 v[42:45], v[206:209], v[190:193], v[42:45]
	ds_read_b128 v[102:105], v226 offset:4096
	ds_read_b128 v[106:109], v226 offset:6144
	v_mfma_f32_16x16x32_bf16 v[38:41], v[210:213], v[190:193], v[38:41]
	ds_read_b128 v[110:113], v227 offset:16384
	ds_read_b128 v[114:117], v227 offset:18432
	v_mfma_f32_16x16x32_bf16 v[34:37], v[214:217], v[190:193], v[34:37]
	ds_read_b128 v[118:121], v227 offset:20480
	ds_read_b128 v[122:125], v227 offset:22528
	v_mfma_f32_16x16x32_bf16 v[30:33], v[202:205], v[194:197], v[30:33]
	ds_read_b128 v[126:129], v91 offset:0
	ds_read_b128 v[130:133], v91 offset:2048
	v_mfma_f32_16x16x32_bf16 v[26:29], v[206:209], v[194:197], v[26:29]
	ds_read_b128 v[134:137], v91 offset:4096
	ds_read_b128 v[138:141], v91 offset:6144
	v_mfma_f32_16x16x32_bf16 v[22:25], v[210:213], v[194:197], v[22:25]
	ds_read_b128 v[142:145], v92 offset:16384
	ds_read_b128 v[152:155], v92 offset:18432
	v_mfma_f32_16x16x32_bf16 v[18:21], v[214:217], v[194:197], v[18:21]
	ds_read_b128 v[156:159], v92 offset:20480
	ds_read_b128 v[178:181], v92 offset:22528
	v_mfma_f32_16x16x32_bf16 v[14:17], v[202:205], v[198:201], v[14:17]
	v_mfma_f32_16x16x32_bf16 v[10:13], v[206:209], v[198:201], v[10:13]
	v_mfma_f32_16x16x32_bf16 v[6:9], v[210:213], v[198:201], v[6:9]
	v_mfma_f32_16x16x32_bf16 v[2:5], v[214:217], v[198:201], v[2:5]
	v_mfma_f32_16x16x32_bf16 v[62:65], a[0:3], v[218:221], v[62:65]
	v_mfma_f32_16x16x32_bf16 v[58:61], a[4:7], v[218:221], v[58:61]
	v_mfma_f32_16x16x32_bf16 v[54:57], a[8:11], v[218:221], v[54:57]
	v_mfma_f32_16x16x32_bf16 v[50:53], a[12:15], v[218:221], v[50:53]
	s_setprio 0
	s_waitcnt lgkmcnt(0)
	s_barrier
	s_and_b32 s4, s34, 0x3c0
	s_lshl_b32 s6, s4, 1
	s_add_u32 s4, s39, s6
	s_addc_u32 s5, s45, 0
	s_add_u32 s6, s49, s6
	s_addc_u32 s7, s51, 0
	s_add_i32 s34, s34, 64
	s_setprio 1
	s_add_u32 m0, s100, 0x0
	v_mfma_f32_16x16x32_bf16 v[46:49], a[0:3], v[222:225], v[46:49]
	global_load_lds_dwordx4 v70, s[4:5]
	s_add_u32 m0, s100, 0x4000
	v_mfma_f32_16x16x32_bf16 v[42:45], a[4:7], v[222:225], v[42:45]
	global_load_lds_dwordx4 v70, s[6:7]
	s_add_u32 m0, s100, 0x1000
	v_mfma_f32_16x16x32_bf16 v[38:41], a[8:11], v[222:225], v[38:41]
	global_load_lds_dwordx4 v72, s[4:5]
	s_add_u32 m0, s100, 0x5000
	v_mfma_f32_16x16x32_bf16 v[34:37], a[12:15], v[222:225], v[34:37]
	global_load_lds_dwordx4 v72, s[6:7]
	s_add_u32 m0, s100, 0x2000
	v_mfma_f32_16x16x32_bf16 v[30:33], a[0:3], v[78:81], v[30:33]
	global_load_lds_dwordx4 v74, s[4:5]
	s_add_u32 m0, s100, 0x6000
	v_mfma_f32_16x16x32_bf16 v[26:29], a[4:7], v[78:81], v[26:29]
	global_load_lds_dwordx4 v74, s[6:7]
	s_add_u32 m0, s100, 0x3000
	v_mfma_f32_16x16x32_bf16 v[22:25], a[8:11], v[78:81], v[22:25]
	global_load_lds_dwordx4 v76, s[4:5]
	s_add_u32 m0, s100, 0x7000
	v_mfma_f32_16x16x32_bf16 v[18:21], a[12:15], v[78:81], v[18:21]
	global_load_lds_dwordx4 v76, s[6:7]
	v_mfma_f32_16x16x32_bf16 v[14:17], a[0:3], v[82:85], v[14:17]
	v_mfma_f32_16x16x32_bf16 v[10:13], a[4:7], v[82:85], v[10:13]
	v_mfma_f32_16x16x32_bf16 v[6:9], a[8:11], v[82:85], v[6:9]
	v_mfma_f32_16x16x32_bf16 v[2:5], a[12:15], v[82:85], v[2:5]
	s_setprio 0
	s_add_i32 s46, s46, -1
	s_cmp_lg_u32 s46, 0
	s_cbranch_scc1 .Lgp_loop
	s_setprio 1
	v_mfma_f32_16x16x32_bf16 v[62:65], v[110:113], v[94:97], v[62:65]
	v_mfma_f32_16x16x32_bf16 v[58:61], v[114:117], v[94:97], v[58:61]
	v_mfma_f32_16x16x32_bf16 v[54:57], v[118:121], v[94:97], v[54:57]
	v_mfma_f32_16x16x32_bf16 v[50:53], v[122:125], v[94:97], v[50:53]
	s_setprio 0
	s_waitcnt vmcnt(8)
	s_barrier
	s_setprio 1
	v_mfma_f32_16x16x32_bf16 v[46:49], v[110:113], v[98:101], v[46:49]
	ds_read_b128 v[186:189], v226 offset:32768
	ds_read_b128 v[190:193], v226 offset:34816
	v_mfma_f32_16x16x32_bf16 v[42:45], v[114:117], v[98:101], v[42:45]
	ds_read_b128 v[194:197], v226 offset:36864
	ds_read_b128 v[198:201], v226 offset:38912
	v_mfma_f32_16x16x32_bf16 v[38:41], v[118:121], v[98:101], v[38:41]
	ds_read_b128 v[202:205], v227 offset:49152
	ds_read_b128 v[206:209], v227 offset:51200
	v_mfma_f32_16x16x32_bf16 v[34:37], v[122:125], v[98:101], v[34:37]
	ds_read_b128 v[210:213], v227 offset:53248
	ds_read_b128 v[214:217], v227 offset:55296
	v_mfma_f32_16x16x32_bf16 v[30:33], v[110:113], v[102:105], v[30:33]
	ds_read_b128 v[218:221], v91 offset:32768
	ds_read_b128 v[222:225], v91 offset:34816
	v_mfma_f32_16x16x32_bf16 v[26:29], v[114:117], v[102:105], v[26:29]
	ds_read_b128 v[78:81], v91 offset:36864
	ds_read_b128 v[82:85], v91 offset:38912
	v_mfma_f32_16x16x32_bf16 v[22:25], v[118:121], v[102:105], v[22:25]
	ds_read_b128 a[0:3], v92 offset:49152
	ds_read_b128 a[4:7], v92 offset:51200
	v_mfma_f32_16x16x32_bf16 v[18:21], v[122:125], v[102:105], v[18:21]
	ds_read_b128 a[8:11], v92 offset:53248
	ds_read_b128 a[12:15], v92 offset:55296
	v_mfma_f32_16x16x32_bf16 v[14:17], v[110:113], v[106:109], v[14:17]
	v_mfma_f32_16x16x32_bf16 v[10:13], v[114:117], v[106:109], v[10:13]
	v_mfma_f32_16x16x32_bf16 v[6:9], v[118:121], v[106:109], v[6:9]
	v_mfma_f32_16x16x32_bf16 v[2:5], v[122:125], v[106:109], v[2:5]
	v_mfma_f32_16x16x32_bf16 v[62:65], v[142:145], v[126:129], v[62:65]
	v_mfma_f32_16x16x32_bf16 v[58:61], v[152:155], v[126:129], v[58:61]
	v_mfma_f32_16x16x32_bf16 v[54:57], v[156:159], v[126:129], v[54:57]
	v_mfma_f32_16x16x32_bf16 v[50:53], v[178:181], v[126:129], v[50:53]
	s_setprio 0
	s_waitcnt lgkmcnt(0)
	s_barrier
; DI void gemm_issue(const GOp& g, int kt, LAS char* stage, int w, int lane) {
;     const int nk = g.K >> 6;
;     const int kk = ((kt + g.krot) & (nk - 1)) * 64;
;     LAS char* base = stage + w * 1024;
; #pragma unroll
;     for (int j = 0; j < 4; ++j) {
;         const int o = (j * 4 + w) * 1024 + lane * 16, row = o >> 7, cs = (o >> 4) & 7, c = cs ^ ((row >> 1) & 7);
;         gload_lds16(g.A + kk + (unsigned)(row * g.lda + c * 8), base + j * 4096);
; template <bool WIDE = false>
; DI void gemm_core(f32x4 (&acc)[4][4], const GOp& g, LAS char* lds, const int tidx, const bool have_first, const bool has_next, const GOp& gn, const bool fw16 = false) {
;     ...
;     for (int kt = 0; kt < nk; ++kt) {
;         if (kt == 0 && have_first && fw16) {
;             asm volatile("s_waitcnt vmcnt(8) lgkmcnt(0)" ::: "memory");
;             __builtin_amdgcn_s_barrier();
;             asm volatile("" ::: "memory");
;         } else {
;             asm volatile("s_waitcnt vmcnt(0)" ::: "memory");
;             __syncthreads();
;         }
;         if (kt + 1 < nk) {
;             LAS char* base = lds + ((kt + 1) & 1) * 32768 + w * 1024;
;             const int kn = ((kt + 1 + g.krot) & (nk - 1)) * 64;
;             const bf16_t* Ak = g.A + kn; const bf16_t* Bk = g.Bt + kn;
; #pragma unroll
;             for (int j = 0; j < 4; ++j) { gload_lds16(Ak + oa[j], base + j * 4096); gload_lds16(Bk + ob[j], base + 16384 + j * 4096); }
;         } else if (has_next) gemm_issue(gn, 0, lds, w, lane);
;         LAS char* st = lds + (kt & 1) * 32768;
;         if constexpr (WIDE) {
;         bf16x8 af[2][4], bfr[2][4];
; #pragma unroll
;         for (int ks = 0; ks < 2; ++ks) {
; #pragma unroll
;             for (int i = 0; i < 4; ++i) af[ks][i] = *(LAS bf16x8*)(st + aoff + i * 2048 + (sw ^ (ks * 64)));
; #pragma unroll
;             for (int i = 0; i < 4; ++i) bfr[ks][i] = *(LAS bf16x8*)(st + boff + i * 2048 + (sw ^ (ks * 64)));
;         }
;         __builtin_amdgcn_sched_barrier(0);
;         __builtin_amdgcn_s_setprio(1);
; #pragma unroll
;         for (int ks = 0; ks < 2; ++ks)
; #pragma unroll
;             for (int mi = 0; mi < 4; ++mi)
; #pragma unroll
;                 for (int ni = 0; ni < 4; ++ni) acc[mi][ni] = __builtin_amdgcn_mfma_f32_16x16x32_bf16(bfr[ks][ni], af[ks][mi], acc[mi][ni], 0, 0, 0);
;         __builtin_amdgcn_s_setprio(0);
	s_and_b32 s4, s34, 0x3c0
	s_lshl_b32 s6, s4, 1
	s_add_u32 s4, s39, s6
	s_addc_u32 s5, s45, 0
	s_add_u32 s6, s49, s6
	s_addc_u32 s7, s51, 0
	s_add_i32 s34, s34, 64
	s_setprio 1
	s_add_u32 m0, s100, 0x8000
	v_mfma_f32_16x16x32_bf16 v[46:49], v[142:145], v[130:133], v[46:49]
	global_load_lds_dwordx4 v70, s[4:5]
	s_add_u32 m0, s100, 0xc000
	v_mfma_f32_16x16x32_bf16 v[42:45], v[152:155], v[130:133], v[42:45]
	global_load_lds_dwordx4 v70, s[6:7]
	s_add_u32 m0, s100, 0x9000
	v_mfma_f32_16x16x32_bf16 v[38:41], v[156:159], v[130:133], v[38:41]
	global_load_lds_dwordx4 v72, s[4:5]
	s_add_u32 m0, s100, 0xd000
	v_mfma_f32_16x16x32_bf16 v[34:37], v[178:181], v[130:133], v[34:37]
	global_load_lds_dwordx4 v72, s[6:7]
	s_add_u32 m0, s100, 0xa000
	v_mfma_f32_16x16x32_bf16 v[30:33], v[142:145], v[134:137], v[30:33]
	global_load_lds_dwordx4 v74, s[4:5]
	s_add_u32 m0, s100, 0xe000
	v_mfma_f32_16x16x32_bf16 v[26:29], v[152:155], v[134:137], v[26:29]
	global_load_lds_dwordx4 v74, s[6:7]
	s_add_u32 m0, s100, 0xb000
	v_mfma_f32_16x16x32_bf16 v[22:25], v[156:159], v[134:137], v[22:25]
	global_load_lds_dwordx4 v76, s[4:5]
	s_add_u32 m0, s100, 0xf000
	v_mfma_f32_16x16x32_bf16 v[18:21], v[178:181], v[134:137], v[18:21]
	global_load_lds_dwordx4 v76, s[6:7]
	v_mfma_f32_16x16x32_bf16 v[14:17], v[142:145], v[138:141], v[14:17]
	v_mfma_f32_16x16x32_bf16 v[10:13], v[152:155], v[138:141], v[10:13]
	v_mfma_f32_16x16x32_bf16 v[6:9], v[156:159], v[138:141], v[6:9]
	v_mfma_f32_16x16x32_bf16 v[2:5], v[178:181], v[138:141], v[2:5]
	s_setprio 0
	s_setprio 1
	v_mfma_f32_16x16x32_bf16 v[62:65], v[202:205], v[186:189], v[62:65]
	v_mfma_f32_16x16x32_bf16 v[58:61], v[206:209], v[186:189], v[58:61]
	v_mfma_f32_16x16x32_bf16 v[54:57], v[210:213], v[186:189], v[54:57]
	v_mfma_f32_16x16x32_bf16 v[50:53], v[214:217], v[186:189], v[50:53]
	s_setprio 0
	s_waitcnt vmcnt(8)
	s_barrier
	s_setprio 1
	v_mfma_f32_16x16x32_bf16 v[46:49], v[202:205], v[190:193], v[46:49]
	ds_read_b128 v[94:97], v226 offset:0
	ds_read_b128 v[98:101], v226 offset:2048
	v_mfma_f32_16x16x32_bf16 v[42:45], v[206:209], v[190:193], v[42:45]
	ds_read_b128 v[102:105], v226 offset:4096
	ds_read_b128 v[106:109], v226 offset:6144
	v_mfma_f32_16x16x32_bf16 v[38:41], v[210:213], v[190:193], v[38:41]
	ds_read_b128 v[110:113], v227 offset:16384
	ds_read_b128 v[114:117], v227 offset:18432
	v_mfma_f32_16x16x32_bf16 v[34:37], v[214:217], v[190:193], v[34:37]
	ds_read_b128 v[118:121], v227 offset:20480
	ds_read_b128 v[122:125], v227 offset:22528
	v_mfma_f32_16x16x32_bf16 v[30:33], v[202:205], v[194:197], v[30:33]
	ds_read_b128 v[126:129], v91 offset:0
	ds_read_b128 v[130:133], v91 offset:2048
	v_mfma_f32_16x16x32_bf16 v[26:29], v[206:209], v[194:197], v[26:29]
	ds_read_b128 v[134:137], v91 offset:4096
	ds_read_b128 v[138:141], v91 offset:6144
	v_mfma_f32_16x16x32_bf16 v[22:25], v[210:213], v[194:197], v[22:25]
	ds_read_b128 v[142:145], v92 offset:16384
	ds_read_b128 v[152:155], v92 offset:18432
	v_mfma_f32_16x16x32_bf16 v[18:21], v[214:217], v[194:197], v[18:21]
	ds_read_b128 v[156:159], v92 offset:20480
	ds_read_b128 v[178:181], v92 offset:22528
	v_mfma_f32_16x16x32_bf16 v[14:17], v[202:205], v[198:201], v[14:17]
	v_mfma_f32_16x16x32_bf16 v[10:13], v[206:209], v[198:201], v[10:13]
	v_mfma_f32_16x16x32_bf16 v[6:9], v[210:213], v[198:201], v[6:9]
	v_mfma_f32_16x16x32_bf16 v[2:5], v[214:217], v[198:201], v[2:5]
	v_mfma_f32_16x16x32_bf16 v[62:65], a[0:3], v[218:221], v[62:65]
	v_mfma_f32_16x16x32_bf16 v[58:61], a[4:7], v[218:221], v[58:61]
	v_mfma_f32_16x16x32_bf16 v[54:57], a[8:11], v[218:221], v[54:57]
	v_mfma_f32_16x16x32_bf16 v[50:53], a[12:15], v[218:221], v[50:53]
	s_setprio 0
	s_waitcnt lgkmcnt(0)
	s_barrier
	s_and_b64 vcc, exec, s[42:43]
	s_cbranch_vccz .Lgpk13_ni
	s_add_i32 s4, s38, s44
	s_lshl_b32 s4, s4, 7
	s_and_b32 s4, s4, 0x3c0
	s_lshl_b32 s6, s4, 1
	s_lshl_b32 s4, s38, 18
	s_add_u32 s4, s4, s6
	s_add_u32 s4, s26, s4
	s_addc_u32 s5, s27, 0
	s_lshl_b32 s7, s44, 18
	s_add_u32 s6, s7, s6
	s_add_u32 s6, s0, s6
	s_addc_u32 s7, s1, 0
	s_setprio 1
	s_add_u32 m0, s100, 0x0
	v_mfma_f32_16x16x32_bf16 v[46:49], a[0:3], v[222:225], v[46:49]
	global_load_lds_dwordx4 v70, s[4:5]
	s_add_u32 m0, s100, 0x4000
	v_mfma_f32_16x16x32_bf16 v[42:45], a[4:7], v[222:225], v[42:45]
	global_load_lds_dwordx4 v70, s[6:7]
	s_add_u32 m0, s100, 0x1000
	v_mfma_f32_16x16x32_bf16 v[38:41], a[8:11], v[222:225], v[38:41]
	global_load_lds_dwordx4 v72, s[4:5]
	s_add_u32 m0, s100, 0x5000
	v_mfma_f32_16x16x32_bf16 v[34:37], a[12:15], v[222:225], v[34:37]
	global_load_lds_dwordx4 v72, s[6:7]
	s_add_u32 m0, s100, 0x2000
	v_mfma_f32_16x16x32_bf16 v[30:33], a[0:3], v[78:81], v[30:33]
	global_load_lds_dwordx4 v74, s[4:5]
	s_add_u32 m0, s100, 0x6000
	v_mfma_f32_16x16x32_bf16 v[26:29], a[4:7], v[78:81], v[26:29]
	global_load_lds_dwordx4 v74, s[6:7]
	s_add_u32 m0, s100, 0x3000
	v_mfma_f32_16x16x32_bf16 v[22:25], a[8:11], v[78:81], v[22:25]
	global_load_lds_dwordx4 v76, s[4:5]
	s_add_u32 m0, s100, 0x7000
	v_mfma_f32_16x16x32_bf16 v[18:21], a[12:15], v[78:81], v[18:21]
	global_load_lds_dwordx4 v76, s[6:7]
	v_mfma_f32_16x16x32_bf16 v[14:17], a[0:3], v[82:85], v[14:17]
	v_mfma_f32_16x16x32_bf16 v[10:13], a[4:7], v[82:85], v[10:13]
	v_mfma_f32_16x16x32_bf16 v[6:9], a[8:11], v[82:85], v[6:9]
	v_mfma_f32_16x16x32_bf16 v[2:5], a[12:15], v[82:85], v[2:5]
	s_setprio 0
	s_branch .Lgpk13_dn
.Lgpk13_ni:
	s_setprio 1
	v_mfma_f32_16x16x32_bf16 v[46:49], a[0:3], v[222:225], v[46:49]
	v_mfma_f32_16x16x32_bf16 v[42:45], a[4:7], v[222:225], v[42:45]
	v_mfma_f32_16x16x32_bf16 v[38:41], a[8:11], v[222:225], v[38:41]
	v_mfma_f32_16x16x32_bf16 v[34:37], a[12:15], v[222:225], v[34:37]
	v_mfma_f32_16x16x32_bf16 v[30:33], a[0:3], v[78:81], v[30:33]
	v_mfma_f32_16x16x32_bf16 v[26:29], a[4:7], v[78:81], v[26:29]
	v_mfma_f32_16x16x32_bf16 v[22:25], a[8:11], v[78:81], v[22:25]
	v_mfma_f32_16x16x32_bf16 v[18:21], a[12:15], v[78:81], v[18:21]
	v_mfma_f32_16x16x32_bf16 v[14:17], a[0:3], v[82:85], v[14:17]
	v_mfma_f32_16x16x32_bf16 v[10:13], a[4:7], v[82:85], v[10:13]
	v_mfma_f32_16x16x32_bf16 v[6:9], a[8:11], v[82:85], v[6:9]
	v_mfma_f32_16x16x32_bf16 v[2:5], a[12:15], v[82:85], v[2:5]
	s_setprio 0
.Lgpk13_dn:
	s_setprio 1
	v_mfma_f32_16x16x32_bf16 v[62:65], v[110:113], v[94:97], v[62:65]
	v_mfma_f32_16x16x32_bf16 v[58:61], v[114:117], v[94:97], v[58:61]
	v_mfma_f32_16x16x32_bf16 v[54:57], v[118:121], v[94:97], v[54:57]
	v_mfma_f32_16x16x32_bf16 v[50:53], v[122:125], v[94:97], v[50:53]
	s_setprio 0
	s_and_b64 vcc, exec, s[42:43]
	s_cbranch_vccz .Lgpk14rt_w0
	s_waitcnt vmcnt(8)
	s_branch .Lgpk14rt_wd

; DI void gemm_issue(const GOp& g, int kt, LAS char* stage, int w, int lane) {
;     const int nk = g.K >> 6;
;     const int kk = ((kt + g.krot) & (nk - 1)) * 64;
;     LAS char* base = stage + w * 1024;
; #pragma unroll
;     for (int j = 0; j < 4; ++j) {
;         const int o = (j * 4 + w) * 1024 + lane * 16, row = o >> 7, cs = (o >> 4) & 7, c = cs ^ ((row >> 1) & 7);
;         gload_lds16(g.A + kk + (unsigned)(row * g.lda + c * 8), base + j * 4096);
; template <bool WIDE = false>
; DI void gemm_core(f32x4 (&acc)[4][4], const GOp& g, LAS char* lds, const int tidx, const bool have_first, const bool has_next, const GOp& gn, const bool fw16 = false) {
;     ...
;     for (int kt = 0; kt < nk; ++kt) {
;         if (kt == 0 && have_first && fw16) {
;             asm volatile("s_waitcnt vmcnt(8) lgkmcnt(0)" ::: "memory");
;             __builtin_amdgcn_s_barrier();
;             asm volatile("" ::: "memory");
;         } else {
;             asm volatile("s_waitcnt vmcnt(0)" ::: "memory");
;             __syncthreads();
;         }
;         if (kt + 1 < nk) {
;             LAS char* base = lds + ((kt + 1) & 1) * 32768 + w * 1024;
;             const int kn = ((kt + 1 + g.krot) & (nk - 1)) * 64;
;             const bf16_t* Ak = g.A + kn; const bf16_t* Bk = g.Bt + kn;
; #pragma unroll
;             for (int j = 0; j < 4; ++j) { gload_lds16(Ak + oa[j], base + j * 4096); gload_lds16(Bk + ob[j], base + 16384 + j * 4096); }
;         } else if (has_next) gemm_issue(gn, 0, lds, w, lane);
;         LAS char* st = lds + (kt & 1) * 32768;
;         if constexpr (WIDE) {
;         bf16x8 af[2][4], bfr[2][4];
; #pragma unroll
;         for (int ks = 0; ks < 2; ++ks) {
; #pragma unroll
;             for (int i = 0; i < 4; ++i) af[ks][i] = *(LAS bf16x8*)(st + aoff + i * 2048 + (sw ^ (ks * 64)));
; #pragma unroll
;             for (int i = 0; i < 4; ++i) bfr[ks][i] = *(LAS bf16x8*)(st + boff + i * 2048 + (sw ^ (ks * 64)));
;         }
;         __builtin_amdgcn_sched_barrier(0);
;         __builtin_amdgcn_s_setprio(1);
; #pragma unroll
;         for (int ks = 0; ks < 2; ++ks)
; #pragma unroll
;             for (int mi = 0; mi < 4; ++mi)
; #pragma unroll
;                 for (int ni = 0; ni < 4; ++ni) acc[mi][ni] = __builtin_amdgcn_mfma_f32_16x16x32_bf16(bfr[ks][ni], af[ks][mi], acc[mi][ni], 0, 0, 0);
;         __builtin_amdgcn_s_setprio(0);
.Lgpk14rt_wd:
	s_barrier
	s_setprio 1
	v_mfma_f32_16x16x32_bf16 v[46:49], v[110:113], v[98:101], v[46:49]
	ds_read_b128 v[186:189], v226 offset:32768
	ds_read_b128 v[190:193], v226 offset:34816
	v_mfma_f32_16x16x32_bf16 v[42:45], v[114:117], v[98:101], v[42:45]
	ds_read_b128 v[194:197], v226 offset:36864
	ds_read_b128 v[198:201], v226 offset:38912
	v_mfma_f32_16x16x32_bf16 v[38:41], v[118:121], v[98:101], v[38:41]
	ds_read_b128 v[202:205], v227 offset:49152
	ds_read_b128 v[206:209], v227 offset:51200
	v_mfma_f32_16x16x32_bf16 v[34:37], v[122:125], v[98:101], v[34:37]
	ds_read_b128 v[210:213], v227 offset:53248
	ds_read_b128 v[214:217], v227 offset:55296
	v_mfma_f32_16x16x32_bf16 v[30:33], v[110:113], v[102:105], v[30:33]
	ds_read_b128 v[218:221], v91 offset:32768
	ds_read_b128 v[222:225], v91 offset:34816
	v_mfma_f32_16x16x32_bf16 v[26:29], v[114:117], v[102:105], v[26:29]
	ds_read_b128 v[78:81], v91 offset:36864
	ds_read_b128 v[82:85], v91 offset:38912
	v_mfma_f32_16x16x32_bf16 v[22:25], v[118:121], v[102:105], v[22:25]
	ds_read_b128 a[0:3], v92 offset:49152
	ds_read_b128 a[4:7], v92 offset:51200
	v_mfma_f32_16x16x32_bf16 v[18:21], v[122:125], v[102:105], v[18:21]
	ds_read_b128 a[8:11], v92 offset:53248
	ds_read_b128 a[12:15], v92 offset:55296
	v_mfma_f32_16x16x32_bf16 v[14:17], v[110:113], v[106:109], v[14:17]
	v_mfma_f32_16x16x32_bf16 v[10:13], v[114:117], v[106:109], v[10:13]
	v_mfma_f32_16x16x32_bf16 v[6:9], v[118:121], v[106:109], v[6:9]
	v_mfma_f32_16x16x32_bf16 v[2:5], v[122:125], v[106:109], v[2:5]
	v_mfma_f32_16x16x32_bf16 v[62:65], v[142:145], v[126:129], v[62:65]
	v_mfma_f32_16x16x32_bf16 v[58:61], v[152:155], v[126:129], v[58:61]
	v_mfma_f32_16x16x32_bf16 v[54:57], v[156:159], v[126:129], v[54:57]
	v_mfma_f32_16x16x32_bf16 v[50:53], v[178:181], v[126:129], v[50:53]
	s_setprio 0
	s_waitcnt lgkmcnt(0)
	s_barrier
	s_and_b64 vcc, exec, s[42:43]
	s_cbranch_vccz .Lgpk14_ni
	s_add_i32 s4, s38, s44
	s_lshl_b32 s4, s4, 7
	s_add_i32 s4, s4, 64
	s_and_b32 s4, s4, 0x3c0
	s_lshl_b32 s6, s4, 1
	s_lshl_b32 s4, s38, 18
	s_add_u32 s4, s4, s6
	s_add_u32 s4, s26, s4
	s_addc_u32 s5, s27, 0
	s_lshl_b32 s7, s44, 18
	s_add_u32 s6, s7, s6
	s_add_u32 s6, s0, s6
	s_addc_u32 s7, s1, 0
	s_setprio 1
	s_add_u32 m0, s100, 0x8000
	v_mfma_f32_16x16x32_bf16 v[46:49], v[142:145], v[130:133], v[46:49]
	global_load_lds_dwordx4 v70, s[4:5]
	s_add_u32 m0, s100, 0xc000
	v_mfma_f32_16x16x32_bf16 v[42:45], v[152:155], v[130:133], v[42:45]
	global_load_lds_dwordx4 v70, s[6:7]
	s_add_u32 m0, s100, 0x9000
	v_mfma_f32_16x16x32_bf16 v[38:41], v[156:159], v[130:133], v[38:41]
	global_load_lds_dwordx4 v72, s[4:5]
	s_add_u32 m0, s100, 0xd000
	v_mfma_f32_16x16x32_bf16 v[34:37], v[178:181], v[130:133], v[34:37]
	global_load_lds_dwordx4 v72, s[6:7]
	s_add_u32 m0, s100, 0xa000
	v_mfma_f32_16x16x32_bf16 v[30:33], v[142:145], v[134:137], v[30:33]
	global_load_lds_dwordx4 v74, s[4:5]
	s_add_u32 m0, s100, 0xe000
	v_mfma_f32_16x16x32_bf16 v[26:29], v[152:155], v[134:137], v[26:29]
	global_load_lds_dwordx4 v74, s[6:7]
	s_add_u32 m0, s100, 0xb000
	v_mfma_f32_16x16x32_bf16 v[22:25], v[156:159], v[134:137], v[22:25]
	global_load_lds_dwordx4 v76, s[4:5]
	s_add_u32 m0, s100, 0xf000
	v_mfma_f32_16x16x32_bf16 v[18:21], v[178:181], v[134:137], v[18:21]
	global_load_lds_dwordx4 v76, s[6:7]
	v_mfma_f32_16x16x32_bf16 v[14:17], v[142:145], v[138:141], v[14:17]
	v_mfma_f32_16x16x32_bf16 v[10:13], v[152:155], v[138:141], v[10:13]
	v_mfma_f32_16x16x32_bf16 v[6:9], v[156:159], v[138:141], v[6:9]
	v_mfma_f32_16x16x32_bf16 v[2:5], v[178:181], v[138:141], v[2:5]
	s_setprio 0
	s_branch .Lgpk14_dn
.Lgpk14_ni:
	s_setprio 1
	v_mfma_f32_16x16x32_bf16 v[46:49], v[142:145], v[130:133], v[46:49]
	v_mfma_f32_16x16x32_bf16 v[42:45], v[152:155], v[130:133], v[42:45]
	v_mfma_f32_16x16x32_bf16 v[38:41], v[156:159], v[130:133], v[38:41]
	v_mfma_f32_16x16x32_bf16 v[34:37], v[178:181], v[130:133], v[34:37]
	v_mfma_f32_16x16x32_bf16 v[30:33], v[142:145], v[134:137], v[30:33]
	v_mfma_f32_16x16x32_bf16 v[26:29], v[152:155], v[134:137], v[26:29]
	v_mfma_f32_16x16x32_bf16 v[22:25], v[156:159], v[134:137], v[22:25]
	v_mfma_f32_16x16x32_bf16 v[18:21], v[178:181], v[134:137], v[18:21]
	v_mfma_f32_16x16x32_bf16 v[14:17], v[142:145], v[138:141], v[14:17]
	v_mfma_f32_16x16x32_bf16 v[10:13], v[152:155], v[138:141], v[10:13]
	v_mfma_f32_16x16x32_bf16 v[6:9], v[156:159], v[138:141], v[6:9]
	v_mfma_f32_16x16x32_bf16 v[2:5], v[178:181], v[138:141], v[2:5]
	s_setprio 0
.Lgpk14_dn:
	s_and_b64 vcc, exec, s[42:43]
	s_cbranch_vccz .Lgpk15_nr
	s_setprio 1
	v_mfma_f32_16x16x32_bf16 v[62:65], v[202:205], v[186:189], v[62:65]
	v_mfma_f32_16x16x32_bf16 v[58:61], v[206:209], v[186:189], v[58:61]
	v_mfma_f32_16x16x32_bf16 v[54:57], v[210:213], v[186:189], v[54:57]
	v_mfma_f32_16x16x32_bf16 v[50:53], v[214:217], v[186:189], v[50:53]
	s_setprio 0
	s_and_b64 vcc, exec, s[42:43]
	s_cbranch_vccz .Lgpk15rt_w0
	s_waitcnt vmcnt(8)
	s_branch .Lgpk15rt_wd

; #define LAS __attribute__((address_space(3)))
; DI void gload_lds16(const void* g, LAS char* l) { __builtin_amdgcn_global_load_lds((const unsigned*)g, (LAS unsigned*)l, 16, 0, 0); }
; template <bool WIDE = false>
; DI void gemm_core(f32x4 (&acc)[4][4], const GOp& g, LAS char* lds, const int tidx, const bool have_first, const bool has_next, const GOp& gn, const bool fw16 = false) {
;     ...
;     for (int kt = 0; kt < nk; ++kt) {
;         if (kt == 0 && have_first && fw16) {
;             asm volatile("s_waitcnt vmcnt(8) lgkmcnt(0)" ::: "memory");
;             __builtin_amdgcn_s_barrier();
;             asm volatile("" ::: "memory");
;         } else {
;             asm volatile("s_waitcnt vmcnt(0)" ::: "memory");
;             __syncthreads();
;         }
;         if (kt + 1 < nk) {
;             LAS char* base = lds + ((kt + 1) & 1) * 32768 + w * 1024;
;             const int kn = ((kt + 1 + g.krot) & (nk - 1)) * 64;
;             const bf16_t* Ak = g.A + kn; const bf16_t* Bk = g.Bt + kn;
; #pragma unroll
;             for (int j = 0; j < 4; ++j) { gload_lds16(Ak + oa[j], base + j * 4096); gload_lds16(Bk + ob[j], base + 16384 + j * 4096); }
;         } else if (has_next) gemm_issue(gn, 0, lds, w, lane);
;         LAS char* st = lds + (kt & 1) * 32768;
;         if constexpr (WIDE) {
;         bf16x8 af[2][4], bfr[2][4];
; #pragma unroll
;         for (int ks = 0; ks < 2; ++ks) {
; #pragma unroll
;             for (int i = 0; i < 4; ++i) af[ks][i] = *(LAS bf16x8*)(st + aoff + i * 2048 + (sw ^ (ks * 64)));
; #pragma unroll
;             for (int i = 0; i < 4; ++i) bfr[ks][i] = *(LAS bf16x8*)(st + boff + i * 2048 + (sw ^ (ks * 64)));
;         }
;         __builtin_amdgcn_sched_barrier(0);
;         __builtin_amdgcn_s_setprio(1);
; #pragma unroll
;         for (int ks = 0; ks < 2; ++ks)
; #pragma unroll
;             for (int mi = 0; mi < 4; ++mi)
; #pragma unroll
;                 for (int ni = 0; ni < 4; ++ni) acc[mi][ni] = __builtin_amdgcn_mfma_f32_16x16x32_bf16(bfr[ks][ni], af[ks][mi], acc[mi][ni], 0, 0, 0);
;         __builtin_amdgcn_s_setprio(0);
.Lgpk15rt_wd:
	s_barrier
	s_setprio 1
	v_mfma_f32_16x16x32_bf16 v[46:49], v[202:205], v[190:193], v[46:49]
	ds_read_b128 v[94:97], v226 offset:0
	ds_read_b128 v[98:101], v226 offset:2048
	v_mfma_f32_16x16x32_bf16 v[42:45], v[206:209], v[190:193], v[42:45]
	ds_read_b128 v[102:105], v226 offset:4096
	ds_read_b128 v[106:109], v226 offset:6144
	v_mfma_f32_16x16x32_bf16 v[38:41], v[210:213], v[190:193], v[38:41]
	ds_read_b128 v[110:113], v227 offset:16384
	ds_read_b128 v[114:117], v227 offset:18432
	v_mfma_f32_16x16x32_bf16 v[34:37], v[214:217], v[190:193], v[34:37]
	ds_read_b128 v[118:121], v227 offset:20480
	ds_read_b128 v[122:125], v227 offset:22528
	v_mfma_f32_16x16x32_bf16 v[30:33], v[202:205], v[194:197], v[30:33]
	ds_read_b128 v[126:129], v91 offset:0
	ds_read_b128 v[130:133], v91 offset:2048
	v_mfma_f32_16x16x32_bf16 v[26:29], v[206:209], v[194:197], v[26:29]
	ds_read_b128 v[134:137], v91 offset:4096
	ds_read_b128 v[138:141], v91 offset:6144
	v_mfma_f32_16x16x32_bf16 v[22:25], v[210:213], v[194:197], v[22:25]
	ds_read_b128 v[142:145], v92 offset:16384
	ds_read_b128 v[152:155], v92 offset:18432
	v_mfma_f32_16x16x32_bf16 v[18:21], v[214:217], v[194:197], v[18:21]
	ds_read_b128 v[156:159], v92 offset:20480
	ds_read_b128 v[178:181], v92 offset:22528
	v_mfma_f32_16x16x32_bf16 v[14:17], v[202:205], v[198:201], v[14:17]
	v_mfma_f32_16x16x32_bf16 v[10:13], v[206:209], v[198:201], v[10:13]
	v_mfma_f32_16x16x32_bf16 v[6:9], v[210:213], v[198:201], v[6:9]
	v_mfma_f32_16x16x32_bf16 v[2:5], v[214:217], v[198:201], v[2:5]
	v_mfma_f32_16x16x32_bf16 v[62:65], a[0:3], v[218:221], v[62:65]
	v_mfma_f32_16x16x32_bf16 v[58:61], a[4:7], v[218:221], v[58:61]
	v_mfma_f32_16x16x32_bf16 v[54:57], a[8:11], v[218:221], v[54:57]
	v_mfma_f32_16x16x32_bf16 v[50:53], a[12:15], v[218:221], v[50:53]
	s_setprio 0
	s_waitcnt lgkmcnt(0)
	s_barrier
	s_branch .Lgpk15_rd
.Lgpk15_nr:
	s_setprio 1
	v_mfma_f32_16x16x32_bf16 v[62:65], v[202:205], v[186:189], v[62:65]
	v_mfma_f32_16x16x32_bf16 v[58:61], v[206:209], v[186:189], v[58:61]
	v_mfma_f32_16x16x32_bf16 v[54:57], v[210:213], v[186:189], v[54:57]
	v_mfma_f32_16x16x32_bf16 v[50:53], v[214:217], v[186:189], v[50:53]
	s_setprio 0
	s_and_b64 vcc, exec, s[42:43]
	s_cbranch_vccz .Lgpk15nt_w0
	s_waitcnt vmcnt(8)
	s_branch .Lgpk15nt_wd

; DI void gemm_issue(const GOp& g, int kt, LAS char* stage, int w, int lane) {
;     const int nk = g.K >> 6;
;     const int kk = ((kt + g.krot) & (nk - 1)) * 64;
;     LAS char* base = stage + w * 1024;
; #pragma unroll
;     for (int j = 0; j < 4; ++j) {
;         const int o = (j * 4 + w) * 1024 + lane * 16, row = o >> 7, cs = (o >> 4) & 7, c = cs ^ ((row >> 1) & 7);
;         gload_lds16(g.A + kk + (unsigned)(row * g.lda + c * 8), base + j * 4096);
; template <bool WIDE = false>
; DI void gemm_core(f32x4 (&acc)[4][4], const GOp& g, LAS char* lds, const int tidx, const bool have_first, const bool has_next, const GOp& gn, const bool fw16 = false) {
;     ...
;     for (int kt = 0; kt < nk; ++kt) {
;         if (kt == 0 && have_first && fw16) {
;             asm volatile("s_waitcnt vmcnt(8) lgkmcnt(0)" ::: "memory");
;             __builtin_amdgcn_s_barrier();
;             asm volatile("" ::: "memory");
;         } else {
;             asm volatile("s_waitcnt vmcnt(0)" ::: "memory");
;             __syncthreads();
;         }
;         if (kt + 1 < nk) {
;             LAS char* base = lds + ((kt + 1) & 1) * 32768 + w * 1024;
;             const int kn = ((kt + 1 + g.krot) & (nk - 1)) * 64;
;             const bf16_t* Ak = g.A + kn; const bf16_t* Bk = g.Bt + kn;
; #pragma unroll
;             for (int j = 0; j < 4; ++j) { gload_lds16(Ak + oa[j], base + j * 4096); gload_lds16(Bk + ob[j], base + 16384 + j * 4096); }
;         } else if (has_next) gemm_issue(gn, 0, lds, w, lane);
;         LAS char* st = lds + (kt & 1) * 32768;
;         if constexpr (WIDE) {
;         bf16x8 af[2][4], bfr[2][4];
; #pragma unroll
;         for (int ks = 0; ks < 2; ++ks) {
; #pragma unroll
;             for (int i = 0; i < 4; ++i) af[ks][i] = *(LAS bf16x8*)(st + aoff + i * 2048 + (sw ^ (ks * 64)));
; #pragma unroll
;             for (int i = 0; i < 4; ++i) bfr[ks][i] = *(LAS bf16x8*)(st + boff + i * 2048 + (sw ^ (ks * 64)));
;         }
;         __builtin_amdgcn_sched_barrier(0);
;         __builtin_amdgcn_s_setprio(1);
; #pragma unroll
;         for (int ks = 0; ks < 2; ++ks)
; #pragma unroll
;             for (int mi = 0; mi < 4; ++mi)
; #pragma unroll
;                 for (int ni = 0; ni < 4; ++ni) acc[mi][ni] = __builtin_amdgcn_mfma_f32_16x16x32_bf16(bfr[ks][ni], af[ks][mi], acc[mi][ni], 0, 0, 0);
;         __builtin_amdgcn_s_setprio(0);
.Lgpk15nt_wd:
	s_barrier
	s_setprio 1
	v_mfma_f32_16x16x32_bf16 v[46:49], v[202:205], v[190:193], v[46:49]
	v_mfma_f32_16x16x32_bf16 v[42:45], v[206:209], v[190:193], v[42:45]
	v_mfma_f32_16x16x32_bf16 v[38:41], v[210:213], v[190:193], v[38:41]
	v_mfma_f32_16x16x32_bf16 v[34:37], v[214:217], v[190:193], v[34:37]
	v_mfma_f32_16x16x32_bf16 v[30:33], v[202:205], v[194:197], v[30:33]
	v_mfma_f32_16x16x32_bf16 v[26:29], v[206:209], v[194:197], v[26:29]
	v_mfma_f32_16x16x32_bf16 v[22:25], v[210:213], v[194:197], v[22:25]
	v_mfma_f32_16x16x32_bf16 v[18:21], v[214:217], v[194:197], v[18:21]
	v_mfma_f32_16x16x32_bf16 v[14:17], v[202:205], v[198:201], v[14:17]
	v_mfma_f32_16x16x32_bf16 v[10:13], v[206:209], v[198:201], v[10:13]
	v_mfma_f32_16x16x32_bf16 v[6:9], v[210:213], v[198:201], v[6:9]
	v_mfma_f32_16x16x32_bf16 v[2:5], v[214:217], v[198:201], v[2:5]
	v_mfma_f32_16x16x32_bf16 v[62:65], a[0:3], v[218:221], v[62:65]
	v_mfma_f32_16x16x32_bf16 v[58:61], a[4:7], v[218:221], v[58:61]
	v_mfma_f32_16x16x32_bf16 v[54:57], a[8:11], v[218:221], v[54:57]
	v_mfma_f32_16x16x32_bf16 v[50:53], a[12:15], v[218:221], v[50:53]
	s_setprio 0
	s_waitcnt lgkmcnt(0)
	s_barrier
.Lgpk15_rd:
	s_and_b64 vcc, exec, s[42:43]
	s_cbranch_vccz .Lgpk15_ni
	s_add_i32 s4, s38, s44
	s_lshl_b32 s4, s4, 7
	s_add_i32 s4, s4, 128
	s_and_b32 s4, s4, 0x3c0
	s_lshl_b32 s6, s4, 1
	s_lshl_b32 s4, s38, 18
	s_add_u32 s4, s4, s6
	s_add_u32 s4, s26, s4
	s_addc_u32 s5, s27, 0
	s_lshl_b32 s7, s44, 18
	s_add_u32 s6, s7, s6
	s_add_u32 s6, s0, s6
	s_addc_u32 s7, s1, 0
	s_setprio 1
	s_add_u32 m0, s100, 0x0
	v_mfma_f32_16x16x32_bf16 v[46:49], a[0:3], v[222:225], v[46:49]
	global_load_lds_dwordx4 v70, s[4:5]
	s_add_u32 m0, s100, 0x4000
	v_mfma_f32_16x16x32_bf16 v[42:45], a[4:7], v[222:225], v[42:45]
	global_load_lds_dwordx4 v70, s[6:7]
	s_add_u32 m0, s100, 0x1000
	v_mfma_f32_16x16x32_bf16 v[38:41], a[8:11], v[222:225], v[38:41]
	global_load_lds_dwordx4 v72, s[4:5]
	s_add_u32 m0, s100, 0x5000
	v_mfma_f32_16x16x32_bf16 v[34:37], a[12:15], v[222:225], v[34:37]
	global_load_lds_dwordx4 v72, s[6:7]
	s_add_u32 m0, s100, 0x2000
	v_mfma_f32_16x16x32_bf16 v[30:33], a[0:3], v[78:81], v[30:33]
	global_load_lds_dwordx4 v74, s[4:5]
	s_add_u32 m0, s100, 0x6000
	v_mfma_f32_16x16x32_bf16 v[26:29], a[4:7], v[78:81], v[26:29]
	global_load_lds_dwordx4 v74, s[6:7]
	s_add_u32 m0, s100, 0x3000
	v_mfma_f32_16x16x32_bf16 v[22:25], a[8:11], v[78:81], v[22:25]
	global_load_lds_dwordx4 v76, s[4:5]
	s_add_u32 m0, s100, 0x7000
	v_mfma_f32_16x16x32_bf16 v[18:21], a[12:15], v[78:81], v[18:21]
	global_load_lds_dwordx4 v76, s[6:7]
	v_mfma_f32_16x16x32_bf16 v[14:17], a[0:3], v[82:85], v[14:17]
	v_mfma_f32_16x16x32_bf16 v[10:13], a[4:7], v[82:85], v[10:13]
	v_mfma_f32_16x16x32_bf16 v[6:9], a[8:11], v[82:85], v[6:9]
	v_mfma_f32_16x16x32_bf16 v[2:5], a[12:15], v[82:85], v[2:5]
	s_setprio 0
	s_branch .Lgpk15_dn

; DI float sigm(float x) { return __builtin_amdgcn_rcpf(1.f + __expf(-x)); }
; DI void phase_merge(const Params& p, int l, LAS char* lds) {
;     ...
;         if (gate) {
; #pragma unroll
;             for (int ni = 0; ni < 4; ++ni) {
;                 const f32x4 bv = bvv[ni];
; #pragma unroll
;                 for (int mi = 0; mi < 4; ++mi) {
;                     const f32x4 a = acc[mi][ni] + bv;
;                     const unsigned q0 = (unsigned)(fmaxf(sigm(a[0]) * 255.f, 1.f) + 0.5f), q1 = (unsigned)(fmaxf(sigm(a[1]) * 255.f, 1.f) + 0.5f);
;                     const unsigned q2 = (unsigned)(fmaxf(sigm(a[2]) * 255.f, 1.f) + 0.5f), q3 = (unsigned)(fmaxf(sigm(a[3]) * 255.f, 1.f) + 0.5f);
;                     st[(mi * 4 + ni) * 256] = q0 | (q1 << 8) | (q2 << 16) | (q3 << 24);
;                 }
;             }
.Lgpk15_dn:
	s_lshl_b32 s5, s55, 2
	s_add_u32 s5, s5, s54
	s_lshl_b32 s5, s5, 14
	s_add_u32 s58, s60, s5
	s_addc_u32 s59, s61, 0
	v_add_f32_e32 v186, v66, v62
	v_add_f32_e32 v187, v68, v63
	v_add_f32_e32 v188, v69, v64
	v_add_f32_e32 v189, v93, v65
	v_mul_f32_e32 v186, 0xbfb8aa3b, v186
	v_mul_f32_e32 v187, 0xbfb8aa3b, v187
	v_mul_f32_e32 v188, 0xbfb8aa3b, v188
	v_mul_f32_e32 v189, 0xbfb8aa3b, v189
	v_exp_f32_e32 v186, v186
	v_exp_f32_e32 v187, v187
	v_exp_f32_e32 v188, v188
	v_exp_f32_e32 v189, v189
	v_add_f32_e32 v186, 1.0, v186
	v_add_f32_e32 v187, 1.0, v187
	v_add_f32_e32 v188, 1.0, v188
	v_add_f32_e32 v189, 1.0, v189
	v_rcp_f32_e32 v186, v186
	v_rcp_f32_e32 v187, v187
	v_rcp_f32_e32 v188, v188
	v_rcp_f32_e32 v189, v189
	v_mul_f32_e32 v186, 0x437f0000, v186
	v_mul_f32_e32 v187, 0x437f0000, v187
	v_mul_f32_e32 v188, 0x437f0000, v188
	v_mul_f32_e32 v189, 0x437f0000, v189
	v_max_f32_e32 v186, 1.0, v186
	v_max_f32_e32 v187, 1.0, v187
	v_max_f32_e32 v188, 1.0, v188
	v_max_f32_e32 v189, 1.0, v189
	v_add_f32_e32 v186, 0.5, v186
	v_add_f32_e32 v187, 0.5, v187
	v_add_f32_e32 v188, 0.5, v188
	v_add_f32_e32 v189, 0.5, v189
	v_cvt_u32_f32_e32 v186, v186
	v_cvt_u32_f32_e32 v187, v187
	v_cvt_u32_f32_sdwa v188, v188 dst_sel:WORD_1 dst_unused:UNUSED_PAD src0_sel:DWORD
	v_cvt_u32_f32_sdwa v189, v189 dst_sel:BYTE_3 dst_unused:UNUSED_PAD src0_sel:DWORD
	v_lshl_or_b32 v186, v187, 8, v186
	s_nop 0
	v_or3_b32 v186, v186, v188, v189
	global_store_dword v1, v186, s[58:59] offset:0
	v_add_f32_e32 v190, v146, v58
	v_add_f32_e32 v191, v147, v59
	v_add_f32_e32 v192, v148, v60
	v_add_f32_e32 v193, v160, v61
	v_mul_f32_e32 v190, 0xbfb8aa3b, v190
	v_mul_f32_e32 v191, 0xbfb8aa3b, v191
	v_mul_f32_e32 v192, 0xbfb8aa3b, v192
	v_mul_f32_e32 v193, 0xbfb8aa3b, v193
	v_exp_f32_e32 v190, v190
	v_exp_f32_e32 v191, v191
	v_exp_f32_e32 v192, v192
	v_exp_f32_e32 v193, v193
	v_add_f32_e32 v190, 1.0, v190
	v_add_f32_e32 v191, 1.0, v191
	v_add_f32_e32 v192, 1.0, v192
	v_add_f32_e32 v193, 1.0, v193
	v_rcp_f32_e32 v190, v190
	v_rcp_f32_e32 v191, v191
	v_rcp_f32_e32 v192, v192
	v_rcp_f32_e32 v193, v193
	v_mul_f32_e32 v190, 0x437f0000, v190
	v_mul_f32_e32 v191, 0x437f0000, v191
	v_mul_f32_e32 v192, 0x437f0000, v192
	v_mul_f32_e32 v193, 0x437f0000, v193
	v_max_f32_e32 v190, 1.0, v190
	v_max_f32_e32 v191, 1.0, v191
	v_max_f32_e32 v192, 1.0, v192
	v_max_f32_e32 v193, 1.0, v193
	v_add_f32_e32 v190, 0.5, v190
	v_add_f32_e32 v191, 0.5, v191
	v_add_f32_e32 v192, 0.5, v192
	v_add_f32_e32 v193, 0.5, v193
	v_cvt_u32_f32_e32 v190, v190
	v_cvt_u32_f32_e32 v191, v191
	v_cvt_u32_f32_sdwa v192, v192 dst_sel:WORD_1 dst_unused:UNUSED_PAD src0_sel:DWORD
	v_cvt_u32_f32_sdwa v193, v193 dst_sel:BYTE_3 dst_unused:UNUSED_PAD src0_sel:DWORD
	v_lshl_or_b32 v190, v191, 8, v190
	s_nop 0
	v_or3_b32 v190, v190, v192, v193
	global_store_dword v1, v190, s[58:59] offset:1024
	v_add_f32_e32 v186, v161, v54
	v_add_f32_e32 v187, v182, v55
	v_add_f32_e32 v188, v183, v56
	v_add_f32_e32 v189, v184, v57
	v_mul_f32_e32 v186, 0xbfb8aa3b, v186
	v_mul_f32_e32 v187, 0xbfb8aa3b, v187
	v_mul_f32_e32 v188, 0xbfb8aa3b, v188
	v_mul_f32_e32 v189, 0xbfb8aa3b, v189
	v_exp_f32_e32 v186, v186
	v_exp_f32_e32 v187, v187
	v_exp_f32_e32 v188, v188
	v_exp_f32_e32 v189, v189
	v_add_f32_e32 v186, 1.0, v186
	v_add_f32_e32 v187, 1.0, v187
	v_add_f32_e32 v188, 1.0, v188
	v_add_f32_e32 v189, 1.0, v189
	v_rcp_f32_e32 v186, v186
	v_rcp_f32_e32 v187, v187
	v_rcp_f32_e32 v188, v188
	v_rcp_f32_e32 v189, v189
	v_mul_f32_e32 v186, 0x437f0000, v186
	v_mul_f32_e32 v187, 0x437f0000, v187
	v_mul_f32_e32 v188, 0x437f0000, v188
	v_mul_f32_e32 v189, 0x437f0000, v189
	v_max_f32_e32 v186, 1.0, v186
	v_max_f32_e32 v187, 1.0, v187
	v_max_f32_e32 v188, 1.0, v188
	v_max_f32_e32 v189, 1.0, v189
	v_add_f32_e32 v186, 0.5, v186
	v_add_f32_e32 v187, 0.5, v187
	v_add_f32_e32 v188, 0.5, v188
	v_add_f32_e32 v189, 0.5, v189
	v_cvt_u32_f32_e32 v186, v186
	v_cvt_u32_f32_e32 v187, v187
	v_cvt_u32_f32_sdwa v188, v188 dst_sel:WORD_1 dst_unused:UNUSED_PAD src0_sel:DWORD
	v_cvt_u32_f32_sdwa v189, v189 dst_sel:BYTE_3 dst_unused:UNUSED_PAD src0_sel:DWORD
	v_lshl_or_b32 v186, v187, 8, v186
	s_nop 0
	v_or3_b32 v186, v186, v188, v189
	global_store_dword v1, v186, s[58:59] offset:2048
	v_add_f32_e32 v190, v185, v50
	v_add_f32_e32 v191, v71, v51
	v_add_f32_e32 v192, v73, v52
	v_add_f32_e32 v193, v75, v53
	v_mul_f32_e32 v190, 0xbfb8aa3b, v190
	v_mul_f32_e32 v191, 0xbfb8aa3b, v191
	v_mul_f32_e32 v192, 0xbfb8aa3b, v192
	v_mul_f32_e32 v193, 0xbfb8aa3b, v193
	v_exp_f32_e32 v190, v190
	v_exp_f32_e32 v191, v191
	v_exp_f32_e32 v192, v192
	v_exp_f32_e32 v193, v193
	v_add_f32_e32 v190, 1.0, v190
	v_add_f32_e32 v191, 1.0, v191
	v_add_f32_e32 v192, 1.0, v192
	v_add_f32_e32 v193, 1.0, v193
	v_rcp_f32_e32 v190, v190
	v_rcp_f32_e32 v191, v191
	v_rcp_f32_e32 v192, v192
	v_rcp_f32_e32 v193, v193
	v_mul_f32_e32 v190, 0x437f0000, v190
	v_mul_f32_e32 v191, 0x437f0000, v191
	v_mul_f32_e32 v192, 0x437f0000, v192
	v_mul_f32_e32 v193, 0x437f0000, v193
	v_max_f32_e32 v190, 1.0, v190
	v_max_f32_e32 v191, 1.0, v191
	v_max_f32_e32 v192, 1.0, v192
	v_max_f32_e32 v193, 1.0, v193
	v_add_f32_e32 v190, 0.5, v190
	v_add_f32_e32 v191, 0.5, v191
	v_add_f32_e32 v192, 0.5, v192
	v_add_f32_e32 v193, 0.5, v193
	v_cvt_u32_f32_e32 v190, v190
	v_cvt_u32_f32_e32 v191, v191
	v_cvt_u32_f32_sdwa v192, v192 dst_sel:WORD_1 dst_unused:UNUSED_PAD src0_sel:DWORD
	v_cvt_u32_f32_sdwa v193, v193 dst_sel:BYTE_3 dst_unused:UNUSED_PAD src0_sel:DWORD
	v_lshl_or_b32 v190, v191, 8, v190
	s_nop 0
	v_or3_b32 v190, v190, v192, v193
	global_store_dword v1, v190, s[58:59] offset:3072
	s_add_u32 s58, s58, 0x1000
	s_addc_u32 s59, s59, 0
	v_add_f32_e32 v186, v66, v46
; DI float sigm(float x) { return __builtin_amdgcn_rcpf(1.f + __expf(-x)); }
; DI void phase_merge(const Params& p, int l, LAS char* lds) {
;     ...
;         if (gate) {
; #pragma unroll
;             for (int ni = 0; ni < 4; ++ni) {
;                 const f32x4 bv = bvv[ni];
; #pragma unroll
;                 for (int mi = 0; mi < 4; ++mi) {
;                     const f32x4 a = acc[mi][ni] + bv;
;                     const unsigned q0 = (unsigned)(fmaxf(sigm(a[0]) * 255.f, 1.f) + 0.5f), q1 = (unsigned)(fmaxf(sigm(a[1]) * 255.f, 1.f) + 0.5f);
;                     const unsigned q2 = (unsigned)(fmaxf(sigm(a[2]) * 255.f, 1.f) + 0.5f), q3 = (unsigned)(fmaxf(sigm(a[3]) * 255.f, 1.f) + 0.5f);
;                     st[(mi * 4 + ni) * 256] = q0 | (q1 << 8) | (q2 << 16) | (q3 << 24);
;                 }
;             }
	v_add_f32_e32 v187, v68, v47
	v_add_f32_e32 v188, v69, v48
	v_add_f32_e32 v189, v93, v49
	v_mul_f32_e32 v186, 0xbfb8aa3b, v186
	v_mul_f32_e32 v187, 0xbfb8aa3b, v187
	v_mul_f32_e32 v188, 0xbfb8aa3b, v188
	v_mul_f32_e32 v189, 0xbfb8aa3b, v189
	v_exp_f32_e32 v186, v186
	v_exp_f32_e32 v187, v187
	v_exp_f32_e32 v188, v188
	v_exp_f32_e32 v189, v189
	v_add_f32_e32 v186, 1.0, v186
	v_add_f32_e32 v187, 1.0, v187
	v_add_f32_e32 v188, 1.0, v188
	v_add_f32_e32 v189, 1.0, v189
	v_rcp_f32_e32 v186, v186
	v_rcp_f32_e32 v187, v187
	v_rcp_f32_e32 v188, v188
	v_rcp_f32_e32 v189, v189
	v_mul_f32_e32 v186, 0x437f0000, v186
	v_mul_f32_e32 v187, 0x437f0000, v187
	v_mul_f32_e32 v188, 0x437f0000, v188
	v_mul_f32_e32 v189, 0x437f0000, v189
	v_max_f32_e32 v186, 1.0, v186
	v_max_f32_e32 v187, 1.0, v187
	v_max_f32_e32 v188, 1.0, v188
	v_max_f32_e32 v189, 1.0, v189
	v_add_f32_e32 v186, 0.5, v186
	v_add_f32_e32 v187, 0.5, v187
	v_add_f32_e32 v188, 0.5, v188
	v_add_f32_e32 v189, 0.5, v189
	v_cvt_u32_f32_e32 v186, v186
	v_cvt_u32_f32_e32 v187, v187
	v_cvt_u32_f32_sdwa v188, v188 dst_sel:WORD_1 dst_unused:UNUSED_PAD src0_sel:DWORD
	v_cvt_u32_f32_sdwa v189, v189 dst_sel:BYTE_3 dst_unused:UNUSED_PAD src0_sel:DWORD
	v_lshl_or_b32 v186, v187, 8, v186
	s_nop 0
	v_or3_b32 v186, v186, v188, v189
	global_store_dword v1, v186, s[58:59] offset:0
	v_add_f32_e32 v190, v146, v42
	v_add_f32_e32 v191, v147, v43
	v_add_f32_e32 v192, v148, v44
	v_add_f32_e32 v193, v160, v45
	v_mul_f32_e32 v190, 0xbfb8aa3b, v190
	v_mul_f32_e32 v191, 0xbfb8aa3b, v191
	v_mul_f32_e32 v192, 0xbfb8aa3b, v192
	v_mul_f32_e32 v193, 0xbfb8aa3b, v193
	v_exp_f32_e32 v190, v190
	v_exp_f32_e32 v191, v191
	v_exp_f32_e32 v192, v192
	v_exp_f32_e32 v193, v193
	v_add_f32_e32 v190, 1.0, v190
	v_add_f32_e32 v191, 1.0, v191
	v_add_f32_e32 v192, 1.0, v192
	v_add_f32_e32 v193, 1.0, v193
	v_rcp_f32_e32 v190, v190
	v_rcp_f32_e32 v191, v191
	v_rcp_f32_e32 v192, v192
	v_rcp_f32_e32 v193, v193
	v_mul_f32_e32 v190, 0x437f0000, v190
	v_mul_f32_e32 v191, 0x437f0000, v191
	v_mul_f32_e32 v192, 0x437f0000, v192
	v_mul_f32_e32 v193, 0x437f0000, v193
	v_max_f32_e32 v190, 1.0, v190
	v_max_f32_e32 v191, 1.0, v191
	v_max_f32_e32 v192, 1.0, v192
	v_max_f32_e32 v193, 1.0, v193
	v_add_f32_e32 v190, 0.5, v190
	v_add_f32_e32 v191, 0.5, v191
	v_add_f32_e32 v192, 0.5, v192
	v_add_f32_e32 v193, 0.5, v193
	v_cvt_u32_f32_e32 v190, v190
	v_cvt_u32_f32_e32 v191, v191
	v_cvt_u32_f32_sdwa v192, v192 dst_sel:WORD_1 dst_unused:UNUSED_PAD src0_sel:DWORD
	v_cvt_u32_f32_sdwa v193, v193 dst_sel:BYTE_3 dst_unused:UNUSED_PAD src0_sel:DWORD
	v_lshl_or_b32 v190, v191, 8, v190
	s_nop 0
	v_or3_b32 v190, v190, v192, v193
	global_store_dword v1, v190, s[58:59] offset:1024
	v_add_f32_e32 v186, v161, v38
	v_add_f32_e32 v187, v182, v39
	v_add_f32_e32 v188, v183, v40
	v_add_f32_e32 v189, v184, v41
	v_mul_f32_e32 v186, 0xbfb8aa3b, v186
	v_mul_f32_e32 v187, 0xbfb8aa3b, v187
	v_mul_f32_e32 v188, 0xbfb8aa3b, v188
	v_mul_f32_e32 v189, 0xbfb8aa3b, v189
	v_exp_f32_e32 v186, v186
	v_exp_f32_e32 v187, v187
	v_exp_f32_e32 v188, v188
	v_exp_f32_e32 v189, v189
	v_add_f32_e32 v186, 1.0, v186
	v_add_f32_e32 v187, 1.0, v187
	v_add_f32_e32 v188, 1.0, v188
	v_add_f32_e32 v189, 1.0, v189
	v_rcp_f32_e32 v186, v186
	v_rcp_f32_e32 v187, v187
	v_rcp_f32_e32 v188, v188
	v_rcp_f32_e32 v189, v189
	v_mul_f32_e32 v186, 0x437f0000, v186
	v_mul_f32_e32 v187, 0x437f0000, v187
	v_mul_f32_e32 v188, 0x437f0000, v188
	v_mul_f32_e32 v189, 0x437f0000, v189
	v_max_f32_e32 v186, 1.0, v186
	v_max_f32_e32 v187, 1.0, v187
	v_max_f32_e32 v188, 1.0, v188
	v_max_f32_e32 v189, 1.0, v189
	v_add_f32_e32 v186, 0.5, v186
	v_add_f32_e32 v187, 0.5, v187
	v_add_f32_e32 v188, 0.5, v188
	v_add_f32_e32 v189, 0.5, v189
	v_cvt_u32_f32_e32 v186, v186
	v_cvt_u32_f32_e32 v187, v187
	v_cvt_u32_f32_sdwa v188, v188 dst_sel:WORD_1 dst_unused:UNUSED_PAD src0_sel:DWORD
	v_cvt_u32_f32_sdwa v189, v189 dst_sel:BYTE_3 dst_unused:UNUSED_PAD src0_sel:DWORD
	v_lshl_or_b32 v186, v187, 8, v186
	s_nop 0
	v_or3_b32 v186, v186, v188, v189
	global_store_dword v1, v186, s[58:59] offset:2048
	v_add_f32_e32 v190, v185, v34
	v_add_f32_e32 v191, v71, v35
	v_add_f32_e32 v192, v73, v36
	v_add_f32_e32 v193, v75, v37
	v_mul_f32_e32 v190, 0xbfb8aa3b, v190
	v_mul_f32_e32 v191, 0xbfb8aa3b, v191
	v_mul_f32_e32 v192, 0xbfb8aa3b, v192
	v_mul_f32_e32 v193, 0xbfb8aa3b, v193
	v_exp_f32_e32 v190, v190
	v_exp_f32_e32 v191, v191
	v_exp_f32_e32 v192, v192
	v_exp_f32_e32 v193, v193
	v_add_f32_e32 v190, 1.0, v190
	v_add_f32_e32 v191, 1.0, v191
	v_add_f32_e32 v192, 1.0, v192
	v_add_f32_e32 v193, 1.0, v193
	v_rcp_f32_e32 v190, v190
	v_rcp_f32_e32 v191, v191
	v_rcp_f32_e32 v192, v192
	v_rcp_f32_e32 v193, v193
	v_mul_f32_e32 v190, 0x437f0000, v190
	v_mul_f32_e32 v191, 0x437f0000, v191
	v_mul_f32_e32 v192, 0x437f0000, v192
	v_mul_f32_e32 v193, 0x437f0000, v193
	v_max_f32_e32 v190, 1.0, v190
	v_max_f32_e32 v191, 1.0, v191
	v_max_f32_e32 v192, 1.0, v192
	v_max_f32_e32 v193, 1.0, v193
	v_add_f32_e32 v190, 0.5, v190
	v_add_f32_e32 v191, 0.5, v191
	v_add_f32_e32 v192, 0.5, v192
	v_add_f32_e32 v193, 0.5, v193
	v_cvt_u32_f32_e32 v190, v190
	v_cvt_u32_f32_e32 v191, v191
	v_cvt_u32_f32_sdwa v192, v192 dst_sel:WORD_1 dst_unused:UNUSED_PAD src0_sel:DWORD
	v_cvt_u32_f32_sdwa v193, v193 dst_sel:BYTE_3 dst_unused:UNUSED_PAD src0_sel:DWORD
	v_lshl_or_b32 v190, v191, 8, v190
	s_nop 0
	v_or3_b32 v190, v190, v192, v193
	global_store_dword v1, v190, s[58:59] offset:3072
	s_add_u32 s58, s58, 0x1000
	s_addc_u32 s59, s59, 0
	v_add_f32_e32 v186, v66, v30
	v_add_f32_e32 v187, v68, v31
	v_add_f32_e32 v188, v69, v32
	v_add_f32_e32 v189, v93, v33
	v_mul_f32_e32 v186, 0xbfb8aa3b, v186
; DI float sigm(float x) { return __builtin_amdgcn_rcpf(1.f + __expf(-x)); }
; DI void phase_merge(const Params& p, int l, LAS char* lds) {
;     ...
;         if (gate) {
; #pragma unroll
;             for (int ni = 0; ni < 4; ++ni) {
;                 const f32x4 bv = bvv[ni];
; #pragma unroll
;                 for (int mi = 0; mi < 4; ++mi) {
;                     const f32x4 a = acc[mi][ni] + bv;
;                     const unsigned q0 = (unsigned)(fmaxf(sigm(a[0]) * 255.f, 1.f) + 0.5f), q1 = (unsigned)(fmaxf(sigm(a[1]) * 255.f, 1.f) + 0.5f);
;                     const unsigned q2 = (unsigned)(fmaxf(sigm(a[2]) * 255.f, 1.f) + 0.5f), q3 = (unsigned)(fmaxf(sigm(a[3]) * 255.f, 1.f) + 0.5f);
;                     st[(mi * 4 + ni) * 256] = q0 | (q1 << 8) | (q2 << 16) | (q3 << 24);
;                 }
;             }
	v_mul_f32_e32 v187, 0xbfb8aa3b, v187
	v_mul_f32_e32 v188, 0xbfb8aa3b, v188
	v_mul_f32_e32 v189, 0xbfb8aa3b, v189
	v_exp_f32_e32 v186, v186
	v_exp_f32_e32 v187, v187
	v_exp_f32_e32 v188, v188
	v_exp_f32_e32 v189, v189
	v_add_f32_e32 v186, 1.0, v186
	v_add_f32_e32 v187, 1.0, v187
	v_add_f32_e32 v188, 1.0, v188
	v_add_f32_e32 v189, 1.0, v189
	v_rcp_f32_e32 v186, v186
	v_rcp_f32_e32 v187, v187
	v_rcp_f32_e32 v188, v188
	v_rcp_f32_e32 v189, v189
	v_mul_f32_e32 v186, 0x437f0000, v186
	v_mul_f32_e32 v187, 0x437f0000, v187
	v_mul_f32_e32 v188, 0x437f0000, v188
	v_mul_f32_e32 v189, 0x437f0000, v189
	v_max_f32_e32 v186, 1.0, v186
	v_max_f32_e32 v187, 1.0, v187
	v_max_f32_e32 v188, 1.0, v188
	v_max_f32_e32 v189, 1.0, v189
	v_add_f32_e32 v186, 0.5, v186
	v_add_f32_e32 v187, 0.5, v187
	v_add_f32_e32 v188, 0.5, v188
	v_add_f32_e32 v189, 0.5, v189
	v_cvt_u32_f32_e32 v186, v186
	v_cvt_u32_f32_e32 v187, v187
	v_cvt_u32_f32_sdwa v188, v188 dst_sel:WORD_1 dst_unused:UNUSED_PAD src0_sel:DWORD
	v_cvt_u32_f32_sdwa v189, v189 dst_sel:BYTE_3 dst_unused:UNUSED_PAD src0_sel:DWORD
	v_lshl_or_b32 v186, v187, 8, v186
	s_nop 0
	v_or3_b32 v186, v186, v188, v189
	global_store_dword v1, v186, s[58:59] offset:0
	v_add_f32_e32 v190, v146, v26
	v_add_f32_e32 v191, v147, v27
	v_add_f32_e32 v192, v148, v28
	v_add_f32_e32 v193, v160, v29
	v_mul_f32_e32 v190, 0xbfb8aa3b, v190
	v_mul_f32_e32 v191, 0xbfb8aa3b, v191
	v_mul_f32_e32 v192, 0xbfb8aa3b, v192
	v_mul_f32_e32 v193, 0xbfb8aa3b, v193
	v_exp_f32_e32 v190, v190
	v_exp_f32_e32 v191, v191
	v_exp_f32_e32 v192, v192
	v_exp_f32_e32 v193, v193
	v_add_f32_e32 v190, 1.0, v190
	v_add_f32_e32 v191, 1.0, v191
	v_add_f32_e32 v192, 1.0, v192
	v_add_f32_e32 v193, 1.0, v193
	v_rcp_f32_e32 v190, v190
	v_rcp_f32_e32 v191, v191
	v_rcp_f32_e32 v192, v192
	v_rcp_f32_e32 v193, v193
	v_mul_f32_e32 v190, 0x437f0000, v190
	v_mul_f32_e32 v191, 0x437f0000, v191
	v_mul_f32_e32 v192, 0x437f0000, v192
	v_mul_f32_e32 v193, 0x437f0000, v193
	v_max_f32_e32 v190, 1.0, v190
	v_max_f32_e32 v191, 1.0, v191
	v_max_f32_e32 v192, 1.0, v192
	v_max_f32_e32 v193, 1.0, v193
	v_add_f32_e32 v190, 0.5, v190
	v_add_f32_e32 v191, 0.5, v191
	v_add_f32_e32 v192, 0.5, v192
	v_add_f32_e32 v193, 0.5, v193
	v_cvt_u32_f32_e32 v190, v190
	v_cvt_u32_f32_e32 v191, v191
	v_cvt_u32_f32_sdwa v192, v192 dst_sel:WORD_1 dst_unused:UNUSED_PAD src0_sel:DWORD
	v_cvt_u32_f32_sdwa v193, v193 dst_sel:BYTE_3 dst_unused:UNUSED_PAD src0_sel:DWORD
	v_lshl_or_b32 v190, v191, 8, v190
	s_nop 0
	v_or3_b32 v190, v190, v192, v193
	global_store_dword v1, v190, s[58:59] offset:1024
	v_add_f32_e32 v186, v161, v22
	v_add_f32_e32 v187, v182, v23
	v_add_f32_e32 v188, v183, v24
	v_add_f32_e32 v189, v184, v25
	v_mul_f32_e32 v186, 0xbfb8aa3b, v186
	v_mul_f32_e32 v187, 0xbfb8aa3b, v187
	v_mul_f32_e32 v188, 0xbfb8aa3b, v188
	v_mul_f32_e32 v189, 0xbfb8aa3b, v189
	v_exp_f32_e32 v186, v186
	v_exp_f32_e32 v187, v187
	v_exp_f32_e32 v188, v188
	v_exp_f32_e32 v189, v189
	v_add_f32_e32 v186, 1.0, v186
	v_add_f32_e32 v187, 1.0, v187
	v_add_f32_e32 v188, 1.0, v188
	v_add_f32_e32 v189, 1.0, v189
	v_rcp_f32_e32 v186, v186
	v_rcp_f32_e32 v187, v187
	v_rcp_f32_e32 v188, v188
	v_rcp_f32_e32 v189, v189
	v_mul_f32_e32 v186, 0x437f0000, v186
	v_mul_f32_e32 v187, 0x437f0000, v187
	v_mul_f32_e32 v188, 0x437f0000, v188
	v_mul_f32_e32 v189, 0x437f0000, v189
	v_max_f32_e32 v186, 1.0, v186
	v_max_f32_e32 v187, 1.0, v187
	v_max_f32_e32 v188, 1.0, v188
	v_max_f32_e32 v189, 1.0, v189
	v_add_f32_e32 v186, 0.5, v186
	v_add_f32_e32 v187, 0.5, v187
	v_add_f32_e32 v188, 0.5, v188
	v_add_f32_e32 v189, 0.5, v189
	v_cvt_u32_f32_e32 v186, v186
	v_cvt_u32_f32_e32 v187, v187
	v_cvt_u32_f32_sdwa v188, v188 dst_sel:WORD_1 dst_unused:UNUSED_PAD src0_sel:DWORD
	v_cvt_u32_f32_sdwa v189, v189 dst_sel:BYTE_3 dst_unused:UNUSED_PAD src0_sel:DWORD
	v_lshl_or_b32 v186, v187, 8, v186
	s_nop 0
	v_or3_b32 v186, v186, v188, v189
	global_store_dword v1, v186, s[58:59] offset:2048
	v_add_f32_e32 v190, v185, v18
	v_add_f32_e32 v191, v71, v19
	v_add_f32_e32 v192, v73, v20
	v_add_f32_e32 v193, v75, v21
	v_mul_f32_e32 v190, 0xbfb8aa3b, v190
	v_mul_f32_e32 v191, 0xbfb8aa3b, v191
	v_mul_f32_e32 v192, 0xbfb8aa3b, v192
	v_mul_f32_e32 v193, 0xbfb8aa3b, v193
	v_exp_f32_e32 v190, v190
	v_exp_f32_e32 v191, v191
	v_exp_f32_e32 v192, v192
	v_exp_f32_e32 v193, v193
	v_add_f32_e32 v190, 1.0, v190
	v_add_f32_e32 v191, 1.0, v191
	v_add_f32_e32 v192, 1.0, v192
	v_add_f32_e32 v193, 1.0, v193
	v_rcp_f32_e32 v190, v190
	v_rcp_f32_e32 v191, v191
	v_rcp_f32_e32 v192, v192
	v_rcp_f32_e32 v193, v193
	v_mul_f32_e32 v190, 0x437f0000, v190
	v_mul_f32_e32 v191, 0x437f0000, v191
	v_mul_f32_e32 v192, 0x437f0000, v192
	v_mul_f32_e32 v193, 0x437f0000, v193
	v_max_f32_e32 v190, 1.0, v190
	v_max_f32_e32 v191, 1.0, v191
	v_max_f32_e32 v192, 1.0, v192
	v_max_f32_e32 v193, 1.0, v193
	v_add_f32_e32 v190, 0.5, v190
	v_add_f32_e32 v191, 0.5, v191
	v_add_f32_e32 v192, 0.5, v192
	v_add_f32_e32 v193, 0.5, v193
	v_cvt_u32_f32_e32 v190, v190
	v_cvt_u32_f32_e32 v191, v191
	v_cvt_u32_f32_sdwa v192, v192 dst_sel:WORD_1 dst_unused:UNUSED_PAD src0_sel:DWORD
	v_cvt_u32_f32_sdwa v193, v193 dst_sel:BYTE_3 dst_unused:UNUSED_PAD src0_sel:DWORD
	v_lshl_or_b32 v190, v191, 8, v190
	s_nop 0
	v_or3_b32 v190, v190, v192, v193
	global_store_dword v1, v190, s[58:59] offset:3072
	s_add_u32 s58, s58, 0x1000
	s_addc_u32 s59, s59, 0
	v_add_f32_e32 v186, v66, v14
	v_add_f32_e32 v187, v68, v15
	v_add_f32_e32 v188, v69, v16
; DI float sigm(float x) { return __builtin_amdgcn_rcpf(1.f + __expf(-x)); }
; DI void phase_merge(const Params& p, int l, LAS char* lds) {
;     ...
;     for (int f = 0; f < nops; ++f) {
;         const bool gate = f < 4 * ntl;
;         int br, i;
;         if (gate) { br = f / ntl; i = vb + (f - br * ntl) * G; } else { const int f2 = f - 4 * ntl; br = f2 & 3; i = vb + (f2 >> 2) * G; }
;         const int mt = i >> 3, nt = i & 7;
;         const bool has_next = f + 1 < nops;
;         const GOp g = op_of(f), gn = op_of(has_next ? f + 1 : f);
;         unsigned* st = stash + (size_t)(i * 4 + br) * 4096;
;     ...
;         if (gate) {
; #pragma unroll
;             for (int ni = 0; ni < 4; ++ni) {
;                 const f32x4 bv = bvv[ni];
; #pragma unroll
;                 for (int mi = 0; mi < 4; ++mi) {
;                     const f32x4 a = acc[mi][ni] + bv;
;                     const unsigned q0 = (unsigned)(fmaxf(sigm(a[0]) * 255.f, 1.f) + 0.5f), q1 = (unsigned)(fmaxf(sigm(a[1]) * 255.f, 1.f) + 0.5f);
;                     const unsigned q2 = (unsigned)(fmaxf(sigm(a[2]) * 255.f, 1.f) + 0.5f), q3 = (unsigned)(fmaxf(sigm(a[3]) * 255.f, 1.f) + 0.5f);
;                     st[(mi * 4 + ni) * 256] = q0 | (q1 << 8) | (q2 << 16) | (q3 << 24);
;                 }
;             }
	v_add_f32_e32 v189, v93, v17
	v_mul_f32_e32 v186, 0xbfb8aa3b, v186
	v_mul_f32_e32 v187, 0xbfb8aa3b, v187
	v_mul_f32_e32 v188, 0xbfb8aa3b, v188
	v_mul_f32_e32 v189, 0xbfb8aa3b, v189
	v_exp_f32_e32 v186, v186
	v_exp_f32_e32 v187, v187
	v_exp_f32_e32 v188, v188
	v_exp_f32_e32 v189, v189
	v_add_f32_e32 v186, 1.0, v186
	v_add_f32_e32 v187, 1.0, v187
	v_add_f32_e32 v188, 1.0, v188
	v_add_f32_e32 v189, 1.0, v189
	v_rcp_f32_e32 v186, v186
	v_rcp_f32_e32 v187, v187
	v_rcp_f32_e32 v188, v188
	v_rcp_f32_e32 v189, v189
	v_mul_f32_e32 v186, 0x437f0000, v186
	v_mul_f32_e32 v187, 0x437f0000, v187
	v_mul_f32_e32 v188, 0x437f0000, v188
	v_mul_f32_e32 v189, 0x437f0000, v189
	v_max_f32_e32 v186, 1.0, v186
	v_max_f32_e32 v187, 1.0, v187
	v_max_f32_e32 v188, 1.0, v188
	v_max_f32_e32 v189, 1.0, v189
	v_add_f32_e32 v186, 0.5, v186
	v_add_f32_e32 v187, 0.5, v187
	v_add_f32_e32 v188, 0.5, v188
	v_add_f32_e32 v189, 0.5, v189
	v_cvt_u32_f32_e32 v186, v186
	v_cvt_u32_f32_e32 v187, v187
	v_cvt_u32_f32_sdwa v188, v188 dst_sel:WORD_1 dst_unused:UNUSED_PAD src0_sel:DWORD
	v_cvt_u32_f32_sdwa v189, v189 dst_sel:BYTE_3 dst_unused:UNUSED_PAD src0_sel:DWORD
	v_lshl_or_b32 v186, v187, 8, v186
	s_nop 0
	v_or3_b32 v186, v186, v188, v189
	global_store_dword v1, v186, s[58:59] offset:0
	v_add_f32_e32 v190, v146, v10
	v_add_f32_e32 v191, v147, v11
	v_add_f32_e32 v192, v148, v12
	v_add_f32_e32 v193, v160, v13
	v_mul_f32_e32 v190, 0xbfb8aa3b, v190
	v_mul_f32_e32 v191, 0xbfb8aa3b, v191
	v_mul_f32_e32 v192, 0xbfb8aa3b, v192
	v_mul_f32_e32 v193, 0xbfb8aa3b, v193
	v_exp_f32_e32 v190, v190
	v_exp_f32_e32 v191, v191
	v_exp_f32_e32 v192, v192
	v_exp_f32_e32 v193, v193
	v_add_f32_e32 v190, 1.0, v190
	v_add_f32_e32 v191, 1.0, v191
	v_add_f32_e32 v192, 1.0, v192
	v_add_f32_e32 v193, 1.0, v193
	v_rcp_f32_e32 v190, v190
	v_rcp_f32_e32 v191, v191
	v_rcp_f32_e32 v192, v192
	v_rcp_f32_e32 v193, v193
	v_mul_f32_e32 v190, 0x437f0000, v190
	v_mul_f32_e32 v191, 0x437f0000, v191
	v_mul_f32_e32 v192, 0x437f0000, v192
	v_mul_f32_e32 v193, 0x437f0000, v193
	v_max_f32_e32 v190, 1.0, v190
	v_max_f32_e32 v191, 1.0, v191
	v_max_f32_e32 v192, 1.0, v192
	v_max_f32_e32 v193, 1.0, v193
	v_add_f32_e32 v190, 0.5, v190
	v_add_f32_e32 v191, 0.5, v191
	v_add_f32_e32 v192, 0.5, v192
	v_add_f32_e32 v193, 0.5, v193
	v_cvt_u32_f32_e32 v190, v190
	v_cvt_u32_f32_e32 v191, v191
	v_cvt_u32_f32_sdwa v192, v192 dst_sel:WORD_1 dst_unused:UNUSED_PAD src0_sel:DWORD
	v_cvt_u32_f32_sdwa v193, v193 dst_sel:BYTE_3 dst_unused:UNUSED_PAD src0_sel:DWORD
	v_lshl_or_b32 v190, v191, 8, v190
	s_nop 0
	v_or3_b32 v190, v190, v192, v193
	global_store_dword v1, v190, s[58:59] offset:1024
	v_add_f32_e32 v186, v161, v6
	v_add_f32_e32 v187, v182, v7
	v_add_f32_e32 v188, v183, v8
	v_add_f32_e32 v189, v184, v9
	v_mul_f32_e32 v186, 0xbfb8aa3b, v186
	v_mul_f32_e32 v187, 0xbfb8aa3b, v187
	v_mul_f32_e32 v188, 0xbfb8aa3b, v188
	v_mul_f32_e32 v189, 0xbfb8aa3b, v189
	v_exp_f32_e32 v186, v186
	v_exp_f32_e32 v187, v187
	v_exp_f32_e32 v188, v188
	v_exp_f32_e32 v189, v189
	v_add_f32_e32 v186, 1.0, v186
	v_add_f32_e32 v187, 1.0, v187
	v_add_f32_e32 v188, 1.0, v188
	v_add_f32_e32 v189, 1.0, v189
	v_rcp_f32_e32 v186, v186
	v_rcp_f32_e32 v187, v187
	v_rcp_f32_e32 v188, v188
	v_rcp_f32_e32 v189, v189
	v_mul_f32_e32 v186, 0x437f0000, v186
	v_mul_f32_e32 v187, 0x437f0000, v187
	v_mul_f32_e32 v188, 0x437f0000, v188
	v_mul_f32_e32 v189, 0x437f0000, v189
	v_max_f32_e32 v186, 1.0, v186
	v_max_f32_e32 v187, 1.0, v187
	v_max_f32_e32 v188, 1.0, v188
	v_max_f32_e32 v189, 1.0, v189
	v_add_f32_e32 v186, 0.5, v186
	v_add_f32_e32 v187, 0.5, v187
	v_add_f32_e32 v188, 0.5, v188
	v_add_f32_e32 v189, 0.5, v189
	v_cvt_u32_f32_e32 v186, v186
	v_cvt_u32_f32_e32 v187, v187
	v_cvt_u32_f32_sdwa v188, v188 dst_sel:WORD_1 dst_unused:UNUSED_PAD src0_sel:DWORD
	v_cvt_u32_f32_sdwa v189, v189 dst_sel:BYTE_3 dst_unused:UNUSED_PAD src0_sel:DWORD
	v_lshl_or_b32 v186, v187, 8, v186
	s_nop 0
	v_or3_b32 v186, v186, v188, v189
	global_store_dword v1, v186, s[58:59] offset:2048
	v_add_f32_e32 v190, v185, v2
	v_add_f32_e32 v191, v71, v3
	v_add_f32_e32 v192, v73, v4
	v_add_f32_e32 v193, v75, v5
	v_mul_f32_e32 v190, 0xbfb8aa3b, v190
	v_mul_f32_e32 v191, 0xbfb8aa3b, v191
	v_mul_f32_e32 v192, 0xbfb8aa3b, v192
	v_mul_f32_e32 v193, 0xbfb8aa3b, v193
	v_exp_f32_e32 v190, v190
	v_exp_f32_e32 v191, v191
	v_exp_f32_e32 v192, v192
	v_exp_f32_e32 v193, v193
	v_add_f32_e32 v190, 1.0, v190
	v_add_f32_e32 v191, 1.0, v191
	v_add_f32_e32 v192, 1.0, v192
	v_add_f32_e32 v193, 1.0, v193
	v_rcp_f32_e32 v190, v190
	v_rcp_f32_e32 v191, v191
	v_rcp_f32_e32 v192, v192
	v_rcp_f32_e32 v193, v193
	v_mul_f32_e32 v190, 0x437f0000, v190
	v_mul_f32_e32 v191, 0x437f0000, v191
	v_mul_f32_e32 v192, 0x437f0000, v192
	v_mul_f32_e32 v193, 0x437f0000, v193
	v_max_f32_e32 v190, 1.0, v190
	v_max_f32_e32 v191, 1.0, v191
	v_max_f32_e32 v192, 1.0, v192
	v_max_f32_e32 v193, 1.0, v193
	v_add_f32_e32 v190, 0.5, v190
	v_add_f32_e32 v191, 0.5, v191
	v_add_f32_e32 v192, 0.5, v192
	v_add_f32_e32 v193, 0.5, v193
	v_cvt_u32_f32_e32 v190, v190
	v_cvt_u32_f32_e32 v191, v191
	v_cvt_u32_f32_sdwa v192, v192 dst_sel:WORD_1 dst_unused:UNUSED_PAD src0_sel:DWORD
	v_cvt_u32_f32_sdwa v193, v193 dst_sel:BYTE_3 dst_unused:UNUSED_PAD src0_sel:DWORD
	v_lshl_or_b32 v190, v191, 8, v190
	s_nop 0
	v_or3_b32 v190, v190, v192, v193
	global_store_dword v1, v190, s[58:59] offset:3072
	s_mov_b64 s[46:47], -1
	s_mov_b32 s56, s23
	s_and_b64 vcc, exec, s[42:43]
	s_cbranch_vccnz .Lgp_tile
